# prep_gdn head: conv-weight loads hoisted and halo loads batched (no per-load vmcnt(0) drains)
# speedup vs baseline: 1.0255x; 1.0144x over previous
.LBB0_258:
	v_mov_b32_e32 v38, v164
	v_mov_b32_e32 v34, v21
	v_ashrrev_i32_e32 v19, 8, v38
	v_add_u32_e32 v0, s33, v19
	v_bfe_u32 v4, v0, 7, 4
	v_bfe_u32 v136, v38, 7, 1
	v_lshlrev_b32_e32 v107, 1, v4
	v_and_b32_e32 v105, 0x7f, v0
	v_ashrrev_i32_e32 v40, 11, v0
	v_or_b32_e32 v0, v107, v136
	v_and_b32_e32 v32, 0x7f, v38
	v_readlane_b32 s100, v250, 15
	v_readlane_b32 s101, v250, 16
	v_lshrrev_b32_e32 v251, 8, v38
	v_lshlrev_b32_e32 v251, 15, v251
	v_and_b32_e32 v254, 0x80, v38
	v_lshl_add_u32 v251, v254, 6, v251
	v_lshl_add_u32 v251, v4, 9, v251
	v_lshl_add_u32 v251, v32, 2, v251
	global_load_dword v252, v251, s[100:101]
	v_add_u32_e32 v251, 0x10000, v251
	global_load_dword v253, v251, s[100:101]
	v_lshlrev_b32_e32 v127, 7, v0
	v_or_b32_e32 v5, v127, v32
	v_or_b32_e32 v0, 0x1000, v5
	v_subrev_co_u32_e64 v1, s[0:1], 1, v105
	v_lshlrev_b32_e32 v8, 7, v40
	v_add_u32_e32 v1, v1, v8
	v_lshlrev_b32_e32 v20, 1, v0
	s_xor_b64 s[4:5], s[0:1], -1
	v_lshl_add_u32 v1, v1, 1, v1
	v_lshl_add_u64 v[2:3], s[14:15], 0, v[20:21]
	v_mov_b32_e32 v33, 0
	v_mov_b32_e32 v35, 0
	s_and_saveexec_b64 s[6:7], s[4:5]
	s_cbranch_execz .Lpg_hb_done
	s_movk_i32 s2, 0x5000
	v_mad_i64_i32 v[6:7], s[8:9], v1, s2, v[2:3]
	global_load_short_d16_hi v34, v[6:7], off
	v_add_co_u32_e32 v6, vcc, 0x5000, v6
	s_nop 1
	v_addc_co_u32_e32 v7, vcc, 0, v7, vcc
	global_load_short_d16_hi v35, v[6:7], off
	v_add_co_u32_e32 v6, vcc, 0x5000, v6
	s_nop 1
	v_addc_co_u32_e32 v7, vcc, 0, v7, vcc
	global_load_short_d16_hi v33, v[6:7], off
.Lpg_hb_done:
	s_or_b64 exec, exec, s[6:7]
	v_ashrrev_i32_e32 v41, 31, v40
	v_lshlrev_b64 v[36:37], 13, v[40:41]
	v_lshlrev_b32_e32 v20, 1, v0
	v_lshl_or_b32 v22, v105, 6, v36
	v_lshl_add_u64 v[2:3], s[68:69], 0, v[20:21]
	v_mad_u64_u32 v[2:3], s[4:5], v22, s29, v[2:3]
	v_mad_i32_i24 v3, v37, s29, v3
	v_add_co_u32_e32 v6, vcc, s29, v2
	global_load_ushort v84, v[2:3], off
	s_nop 0
	v_addc_co_u32_e32 v7, vcc, 0, v3, vcc
	global_load_ushort v85, v[6:7], off
	v_add_co_u32_e32 v6, vcc, s30, v2
	s_mov_b32 s2, 0x12000
	s_nop 0
	v_addc_co_u32_e32 v7, vcc, 0, v3, vcc
	global_load_ushort v99, v[6:7], off
	v_add_co_u32_e32 v6, vcc, s2, v2
	s_mov_b32 s2, 0x18000
	s_nop 0
	v_addc_co_u32_e32 v7, vcc, 0, v3, vcc
	global_load_ushort v104, v[6:7], off
	v_add_co_u32_e32 v6, vcc, s2, v2
	s_mov_b32 s2, 0x84000
	s_nop 0
	v_addc_co_u32_e32 v7, vcc, 0, v3, vcc
	global_load_ushort v91, v[6:7], off
	v_add_co_u32_e32 v6, vcc, s35, v2
	v_readlane_b32 s36, v250, 3
	s_nop 0
	v_addc_co_u32_e32 v7, vcc, 0, v3, vcc
	global_load_ushort v101, v[6:7], off
	v_add_co_u32_e32 v6, vcc, s60, v2
	v_mov_b32_e32 v1, v21
	s_nop 0
	v_addc_co_u32_e32 v7, vcc, 0, v3, vcc
	global_load_ushort v88, v[6:7], off
	v_add_co_u32_e32 v6, vcc, s61, v2
	v_readlane_b32 s48, v250, 15
	s_nop 0
	v_addc_co_u32_e32 v7, vcc, 0, v3, vcc
	global_load_ushort v93, v[6:7], off
	v_add_co_u32_e32 v6, vcc, s66, v2
	v_readlane_b32 s49, v250, 16
	s_nop 0
	v_addc_co_u32_e32 v7, vcc, 0, v3, vcc
	global_load_ushort v96, v[6:7], off
	v_add_co_u32_e32 v6, vcc, s67, v2
	v_lshl_add_u64 v[0:1], v[0:1], 2, s[48:49]
	s_nop 0
	v_addc_co_u32_e32 v7, vcc, 0, v3, vcc
	global_load_ushort v97, v[6:7], off
	v_add_co_u32_e32 v6, vcc, s64, v2
	v_lshlrev_b32_e32 v20, 2, v5
	s_nop 0
	v_addc_co_u32_e32 v7, vcc, 0, v3, vcc
	global_load_ushort v83, v[6:7], off
	v_add_co_u32_e32 v6, vcc, s65, v2
	global_load_dword v28, v[0:1], off
	s_nop 0
	v_addc_co_u32_e32 v7, vcc, 0, v3, vcc
	global_load_ushort v89, v[6:7], off
	v_add_co_u32_e32 v6, vcc, s74, v2
	v_lshl_add_u64 v[0:1], s[48:49], 0, v[20:21]
	s_nop 0
	v_addc_co_u32_e32 v7, vcc, 0, v3, vcc
	global_load_ushort v78, v[6:7], off
	v_add_co_u32_e32 v6, vcc, s75, v2
	v_lshlrev_b32_e32 v27, 7, v4
	s_nop 0
	v_addc_co_u32_e32 v7, vcc, 0, v3, vcc
	global_load_ushort v81, v[6:7], off
	v_add_co_u32_e32 v6, vcc, s59, v2
	v_readlane_b32 s37, v250, 4
	s_nop 0
	v_addc_co_u32_e32 v7, vcc, 0, v3, vcc
	global_load_ushort v70, v[6:7], off
	v_add_co_u32_e32 v6, vcc, s22, v2
	v_readlane_b32 s38, v250, 5
	s_nop 0
	v_addc_co_u32_e32 v7, vcc, 0, v3, vcc
	global_load_ushort v73, v[6:7], off
	v_add_co_u32_e32 v6, vcc, s23, v2
	v_readlane_b32 s39, v250, 6
	s_nop 0
	v_addc_co_u32_e32 v7, vcc, 0, v3, vcc
	global_load_ushort v75, v[6:7], off
	v_add_co_u32_e32 v6, vcc, s12, v2
	v_readlane_b32 s40, v250, 7
	s_nop 0
	v_addc_co_u32_e32 v7, vcc, 0, v3, vcc
	global_load_ushort v79, v[6:7], off
	v_add_co_u32_e32 v6, vcc, s13, v2
	v_readlane_b32 s41, v250, 8
	s_nop 0
	v_addc_co_u32_e32 v7, vcc, 0, v3, vcc
	global_load_ushort v67, v[6:7], off
	v_add_co_u32_e32 v6, vcc, s28, v2
	v_readlane_b32 s42, v250, 9
	s_nop 0
	v_addc_co_u32_e32 v7, vcc, 0, v3, vcc
	global_load_ushort v71, v[6:7], off
	v_add_co_u32_e32 v6, vcc, s52, v2
	v_readlane_b32 s43, v250, 10
	s_nop 0
	v_addc_co_u32_e32 v7, vcc, 0, v3, vcc
	global_load_ushort v50, v[6:7], off
	v_add_co_u32_e32 v6, vcc, s53, v2
	v_readlane_b32 s44, v250, 11
	s_nop 0
	v_addc_co_u32_e32 v7, vcc, 0, v3, vcc
	global_load_ushort v65, v[6:7], off
	v_add_co_u32_e32 v6, vcc, s2, v2
	s_mov_b32 s2, 0x8a000
	s_nop 0
	v_addc_co_u32_e32 v7, vcc, 0, v3, vcc
	global_load_ushort v41, v[6:7], off
	v_add_co_u32_e32 v6, vcc, s2, v2
	s_mov_b32 s2, 0x90000
	s_nop 0
	v_addc_co_u32_e32 v7, vcc, 0, v3, vcc
	global_load_ushort v51, v[6:7], off
	v_add_co_u32_e32 v6, vcc, s2, v2
	s_mov_b32 s2, 0x96000
	s_nop 0
	v_addc_co_u32_e32 v7, vcc, 0, v3, vcc
	global_load_ushort v59, v[6:7], off
	v_add_co_u32_e32 v6, vcc, s2, v2
	s_mov_b32 s2, 0x9c000
	s_nop 0
	v_addc_co_u32_e32 v7, vcc, 0, v3, vcc
	global_load_ushort v63, v[6:7], off
	v_add_co_u32_e32 v6, vcc, s2, v2
	s_mov_b32 s2, 0xa2000
	s_nop 0
	v_addc_co_u32_e32 v7, vcc, 0, v3, vcc
	global_load_ushort v55, v[6:7], off
	v_add_co_u32_e32 v6, vcc, s2, v2
	s_mov_b32 s2, 0xa8000
	s_nop 0
	v_addc_co_u32_e32 v7, vcc, 0, v3, vcc
	global_load_ushort v58, v[6:7], off
	v_add_co_u32_e32 v6, vcc, s2, v2
	s_mov_b32 s2, 0xae000
	s_nop 0
	v_addc_co_u32_e32 v7, vcc, 0, v3, vcc
	global_load_ushort v53, v[6:7], off
	v_add_co_u32_e32 v6, vcc, s2, v2
	s_mov_b32 s2, 0xb4000
	s_nop 0
	v_addc_co_u32_e32 v7, vcc, 0, v3, vcc
	global_load_ushort v57, v[6:7], off
	v_add_co_u32_e32 v6, vcc, s2, v2
	s_mov_b32 s2, 0xba000
	s_nop 0
	v_addc_co_u32_e32 v7, vcc, 0, v3, vcc
	global_load_ushort v52, v[6:7], off
	v_add_co_u32_e32 v6, vcc, s2, v2
	s_mov_b32 s2, 0xc0000
	s_nop 0
	v_addc_co_u32_e32 v7, vcc, 0, v3, vcc
	global_load_ushort v54, v[6:7], off
	v_add_co_u32_e32 v6, vcc, s2, v2
	s_mov_b32 s2, 0xc6000
	s_nop 0
	v_addc_co_u32_e32 v7, vcc, 0, v3, vcc
	global_load_ushort v56, v[6:7], off
	v_add_co_u32_e32 v6, vcc, s2, v2
	s_mov_b32 s2, 0xcc000
	s_nop 0
	v_addc_co_u32_e32 v7, vcc, 0, v3, vcc
	global_load_ushort v62, v[6:7], off
	v_add_co_u32_e32 v6, vcc, s2, v2
	s_mov_b32 s2, 0xd2000
	s_nop 0
	v_addc_co_u32_e32 v7, vcc, 0, v3, vcc
	global_load_ushort v60, v[6:7], off
	v_add_co_u32_e32 v6, vcc, s2, v2
	s_mov_b32 s2, 0xd8000
	s_nop 0
	v_addc_co_u32_e32 v7, vcc, 0, v3, vcc
	global_load_ushort v61, v[6:7], off
	v_add_co_u32_e32 v6, vcc, s2, v2
	s_mov_b32 s2, 0xde000
	s_nop 0
	v_addc_co_u32_e32 v7, vcc, 0, v3, vcc
	global_load_ushort v64, v[6:7], off
	v_add_co_u32_e32 v6, vcc, s2, v2
	s_mov_b32 s2, 0xe4000
	s_nop 0
	v_addc_co_u32_e32 v7, vcc, 0, v3, vcc
	global_load_ushort v66, v[6:7], off
	v_add_co_u32_e32 v6, vcc, s2, v2
	s_mov_b32 s2, 0xea000
	s_nop 0
	v_addc_co_u32_e32 v7, vcc, 0, v3, vcc
	global_load_ushort v68, v[6:7], off
	v_add_co_u32_e32 v6, vcc, s2, v2
	s_mov_b32 s2, 0xf0000
	s_nop 0
	v_addc_co_u32_e32 v7, vcc, 0, v3, vcc
	global_load_ushort v69, v[6:7], off
	v_add_co_u32_e32 v6, vcc, s2, v2
	s_mov_b32 s2, 0xf6000
	s_nop 0
	v_addc_co_u32_e32 v7, vcc, 0, v3, vcc
	global_load_ushort v72, v[6:7], off
	v_add_co_u32_e32 v6, vcc, s2, v2
	s_mov_b32 s2, 0xfc000
	s_nop 0
	v_addc_co_u32_e32 v7, vcc, 0, v3, vcc
	global_load_ushort v74, v[6:7], off
	v_add_co_u32_e32 v6, vcc, s2, v2
	s_mov_b32 s2, 0x102000
	s_nop 0
	v_addc_co_u32_e32 v7, vcc, 0, v3, vcc
	global_load_ushort v76, v[6:7], off
	v_add_co_u32_e32 v6, vcc, s2, v2
	s_mov_b32 s2, 0x108000
	s_nop 0
	v_addc_co_u32_e32 v7, vcc, 0, v3, vcc
	global_load_ushort v77, v[6:7], off
	v_add_co_u32_e32 v6, vcc, s2, v2
	s_mov_b32 s2, 0x10e000
	s_nop 0
	v_addc_co_u32_e32 v7, vcc, 0, v3, vcc
	global_load_ushort v80, v[6:7], off
	v_add_co_u32_e32 v6, vcc, s2, v2
	s_mov_b32 s2, 0x114000
	s_nop 0
	v_addc_co_u32_e32 v7, vcc, 0, v3, vcc
	global_load_ushort v82, v[6:7], off
	v_add_co_u32_e32 v6, vcc, s2, v2
	s_mov_b32 s2, 0x11a000
	s_nop 0
	v_addc_co_u32_e32 v7, vcc, 0, v3, vcc
	global_load_ushort v86, v[6:7], off
	v_add_co_u32_e32 v6, vcc, s2, v2
	s_mov_b32 s2, 0x120000
	s_nop 0
	v_addc_co_u32_e32 v7, vcc, 0, v3, vcc
	global_load_ushort v87, v[6:7], off
	v_add_co_u32_e32 v6, vcc, s2, v2
	s_mov_b32 s2, 0x126000
	s_nop 0
	v_addc_co_u32_e32 v7, vcc, 0, v3, vcc
	global_load_ushort v90, v[6:7], off
	v_add_co_u32_e32 v6, vcc, s2, v2
	s_mov_b32 s2, 0x12c000
	s_nop 0
	v_addc_co_u32_e32 v7, vcc, 0, v3, vcc
	global_load_ushort v92, v[6:7], off
	v_add_co_u32_e32 v6, vcc, s2, v2
	s_mov_b32 s2, 0x132000
	s_nop 0
	v_addc_co_u32_e32 v7, vcc, 0, v3, vcc
	global_load_ushort v94, v[6:7], off
	v_add_co_u32_e32 v6, vcc, s2, v2
	s_mov_b32 s2, 0x138000
	s_nop 0
	v_addc_co_u32_e32 v7, vcc, 0, v3, vcc
	global_load_ushort v95, v[6:7], off
	v_add_co_u32_e32 v6, vcc, s2, v2
	s_mov_b32 s2, 0x13e000
	s_nop 0
	v_addc_co_u32_e32 v7, vcc, 0, v3, vcc
	global_load_ushort v98, v[6:7], off
	v_add_co_u32_e32 v6, vcc, s2, v2
	s_mov_b32 s2, 0x144000
	s_nop 0
	v_addc_co_u32_e32 v7, vcc, 0, v3, vcc
	global_load_ushort v100, v[6:7], off
	v_add_co_u32_e32 v6, vcc, s2, v2
	s_mov_b32 s2, 0x14a000
	s_nop 0
	v_addc_co_u32_e32 v7, vcc, 0, v3, vcc
	global_load_ushort v102, v[6:7], off
	v_add_co_u32_e32 v6, vcc, s2, v2
	s_mov_b32 s2, 0x150000
	s_nop 0
	v_addc_co_u32_e32 v7, vcc, 0, v3, vcc
	global_load_ushort v103, v[6:7], off
	v_add_co_u32_e32 v6, vcc, s2, v2
	s_mov_b32 s2, 0x156000
	s_nop 0
	v_addc_co_u32_e32 v7, vcc, 0, v3, vcc
	global_load_ushort v106, v[6:7], off
	v_add_co_u32_e32 v6, vcc, s2, v2
	s_mov_b32 s2, 0x15c000
	s_nop 0
	v_addc_co_u32_e32 v7, vcc, 0, v3, vcc
	global_load_ushort v116, v[6:7], off
	v_add_co_u32_e32 v6, vcc, s2, v2
	s_mov_b32 s2, 0x162000
	s_nop 0
	v_addc_co_u32_e32 v7, vcc, 0, v3, vcc
	global_load_ushort v142, v[6:7], off
	v_add_co_u32_e32 v6, vcc, s2, v2
	s_mov_b32 s2, 0x168000
	s_nop 0
	v_addc_co_u32_e32 v7, vcc, 0, v3, vcc
	global_load_ushort v143, v[6:7], off
	v_add_co_u32_e32 v6, vcc, s2, v2
	s_mov_b32 s2, 0x16e000
	s_nop 0
	v_addc_co_u32_e32 v7, vcc, 0, v3, vcc
	global_load_ushort v138, v[6:7], off
	v_add_co_u32_e32 v6, vcc, s2, v2
	s_mov_b32 s2, 0x174000
	s_nop 0
	v_addc_co_u32_e32 v7, vcc, 0, v3, vcc
	global_load_ushort v139, v[6:7], off
	v_add_co_u32_e32 v6, vcc, s2, v2
	s_mov_b32 s2, 0x17a000
	s_nop 0
	v_addc_co_u32_e32 v7, vcc, 0, v3, vcc
	v_add_co_u32_e32 v2, vcc, s2, v2
	global_load_ushort v137, v[6:7], off
	s_nop 0
	v_addc_co_u32_e32 v3, vcc, 0, v3, vcc
	global_load_ushort v207, v[2:3], off
	v_add_co_u32_e32 v2, vcc, s30, v0
	s_movk_i32 s2, 0x400
	s_nop 0
	v_addc_co_u32_e32 v3, vcc, 0, v1, vcc
	global_load_dword v29, v[2:3], off
	v_add_co_u32_e32 v2, vcc, 0x14000, v0
	v_readlane_b32 s45, v250, 12
	s_nop 0
	v_addc_co_u32_e32 v3, vcc, 0, v1, vcc
	v_add_co_u32_e32 v0, vcc, 0x1c000, v0
	global_load_dword v30, v[2:3], off
	s_nop 0
	v_addc_co_u32_e32 v1, vcc, 0, v1, vcc
	global_load_dword v31, v[0:1], off
	v_cmp_gt_i32_e32 vcc, s2, v38
	v_readlane_b32 s46, v250, 13
	v_readlane_b32 s47, v250, 14
	v_readlane_b32 s50, v250, 17
	v_readlane_b32 s51, v250, 18
	s_waitcnt vmcnt(63) expcnt(7) lgkmcnt(15)
	s_barrier
	s_waitcnt vmcnt(63)
	v_lshlrev_b32_e32 v251, 2, v38
	ds_write_b32 v251, v252
	ds_write_b32 v251, v253 offset:2048
	v_readlane_b32 s36, v250, 3
	v_readlane_b32 s37, v250, 4
	v_readlane_b32 s38, v250, 5
	v_readlane_b32 s39, v250, 6
	v_readlane_b32 s40, v250, 7
	v_readlane_b32 s41, v250, 8
	v_readlane_b32 s42, v250, 9
	v_readlane_b32 s43, v250, 10
	v_readlane_b32 s44, v250, 11
	v_readlane_b32 s45, v250, 12
	v_readlane_b32 s46, v250, 13
	v_readlane_b32 s47, v250, 14
	v_readlane_b32 s48, v250, 15
	v_readlane_b32 s49, v250, 16
	v_readlane_b32 s50, v250, 17
	v_readlane_b32 s51, v250, 18
	v_sub_u32_e64 v0, v105, 1 clamp
	v_and_b32_e32 v194, 0xff, v38
	v_or_b32_e32 v12, v0, v8
	v_lshlrev_b32_e32 v39, 6, v105
	v_mad_i64_i32 v[16:17], s[4:5], v12, 3, 0
	v_lshrrev_b32_e32 v24, 4, v194
	v_or_b32_e32 v36, v36, v39
	v_cmp_lt_u32_e32 vcc, 47, v194
	v_mov_b64_e32 v[4:5], 0x20600000
	v_mov_b64_e32 v[2:3], 0x5000
	v_add_u32_e32 v18, -3, v24
	v_mov_b32_e32 v6, v24
	v_mov_b64_e32 v[8:9], v[16:17]
	s_waitcnt lgkmcnt(0)
	s_barrier
	s_and_saveexec_b64 s[4:5], vcc
	v_mov_b64_e32 v[4:5], 0x8100000
	v_mov_b64_e32 v[2:3], 0x6000
	v_mov_b32_e32 v6, v18
	v_mov_b64_e32 v[8:9], v[36:37]
	s_or_b64 exec, exec, s[4:5]
	v_lshlrev_b32_e32 v195, 3, v38
	v_and_b32_e32 v25, 0x78, v195
	v_or_b32_e32 v113, v27, v25
	v_lshlrev_b32_e32 v20, 1, v113
	v_lshl_add_u64 v[4:5], s[82:83], 0, v[4:5]
	v_mov_b32_e32 v7, v21
	v_lshl_add_u64 v[4:5], v[4:5], 0, v[20:21]
	v_lshl_add_u64 v[6:7], v[8:9], 0, v[6:7]
	v_mad_u64_u32 v[4:5], s[4:5], v6, v2, v[4:5]
	v_mov_b32_e32 v6, v5
	v_mad_u64_u32 v[2:3], s[4:5], v7, v2, v[6:7]
	v_cmp_lt_u32_e64 s[4:5], 31, v194
	v_lshl_add_u64 v[0:1], s[14:15], 0, v[20:21]
	v_lshl_add_u64 v[48:49], s[68:69], 0, v[20:21]
	v_cndmask_b32_e64 v10, 1, -2, s[4:5]
	v_mov_b32_e32 v5, v2
	v_cndmask_b32_e64 v3, v17, v37, s[4:5]
	v_cndmask_b32_e64 v2, v16, v36, s[4:5]
	v_add_u32_e32 v20, v10, v24
	v_cndmask_b32_e64 v114, v189, v190, s[4:5]
	v_cndmask_b32_e64 v9, v1, v49, s[4:5]
	v_cndmask_b32_e64 v8, v0, v48, s[4:5]
	v_lshl_add_u64 v[46:47], v[2:3], 0, v[20:21]
	v_mul_lo_u32 v20, v47, v114
	v_mad_u64_u32 v[2:3], s[6:7], v46, v114, v[8:9]
	v_add_u32_e32 v3, v20, v3
	global_load_dwordx4 v[4:7], v[4:5], off
	v_cmp_lt_u32_e64 s[6:7], 15, v194
	global_load_dwordx4 v[8:11], v[2:3], off
	v_add_u32_e32 v42, -1, v24
	s_and_saveexec_b64 s[8:9], s[6:7]
	s_xor_b64 s[8:9], exec, s[8:9]
	v_mov_b32_e32 v43, v21
	v_lshl_add_u64 v[0:1], v[36:37], 0, v[42:43]
	v_mad_u64_u32 v[2:3], s[10:11], v0, s29, v[48:49]
	v_mov_b32_e32 v0, v3
	v_mad_u64_u32 v[0:1], s[10:11], v1, s29, v[0:1]
	v_mov_b32_e32 v3, v0
	s_or_saveexec_b64 s[8:9], s[8:9]
	s_mov_b32 s2, 0xf000
	v_mad_i64_i32 v[44:45], s[10:11], v12, s2, 0
	s_xor_b64 exec, exec, s[8:9]
	v_lshl_add_u64 v[0:1], v[0:1], 0, v[44:45]
	s_mov_b64 s[10:11], 0xa000
	v_lshl_add_u64 v[2:3], v[0:1], 0, s[10:11]
	s_or_b64 exec, exec, s[8:9]
	v_or_b32_e32 v115, v36, v24
	global_load_dwordx4 v[12:15], v[2:3], off
	v_mul_lo_u32 v112, v37, s29
	v_mad_u64_u32 v[0:1], s[8:9], v115, s29, v[48:49]
	v_add_u32_e32 v1, v112, v1
	global_load_dwordx4 v[0:3], v[0:1], off
	v_cmp_gt_u32_e64 s[8:9], 32, v194
	v_cmp_gt_u32_e64 s[10:11], 48, v194
	v_or_b32_e32 v26, v105, v24
	s_and_b64 s[24:25], s[8:9], s[0:1]
	s_and_b64 s[10:11], s[10:11], s[0:1]
	v_lshl_add_u32 v108, v25, 2, 0
	v_cmp_eq_u32_e64 s[0:1], 0, v26
	s_waitcnt vmcnt(2)
	v_cndmask_b32_e64 v26, v8, 0, s[24:25]
	v_cndmask_b32_e64 v117, v9, 0, s[24:25]
	v_cndmask_b32_e64 v8, v11, 0, s[24:25]
	v_cndmask_b32_e64 v111, v5, 0, s[10:11]
	v_cndmask_b32_e64 v9, v6, 0, s[10:11]
	v_cndmask_b32_e64 v5, v7, 0, s[10:11]
	ds_read_b128 v[118:121], v108
	ds_read_b128 v[122:125], v108 offset:16
	ds_read_b128 v[128:131], v108 offset:1024
	ds_read_b128 v[132:135], v108 offset:1040
	ds_read_b128 v[144:147], v108 offset:2048
	ds_read_b128 v[148:151], v108 offset:2064
	ds_read_b128 v[152:155], v108 offset:3072
	ds_read_b128 v[156:159], v108 offset:3088
	v_cndmask_b32_e64 v109, v4, 0, s[10:11]
	v_cndmask_b32_e64 v110, v10, 0, s[24:25]
	v_lshlrev_b32_e32 v4, 16, v5
	v_and_b32_e32 v5, 0xffff0000, v5
	v_lshlrev_b32_e32 v6, 16, v8
	v_and_b32_e32 v7, 0xffff0000, v8
	v_lshlrev_b32_e32 v8, 16, v9
	v_and_b32_e32 v9, 0xffff0000, v9
	v_lshlrev_b32_e32 v10, 16, v110
	v_and_b32_e32 v11, 0xffff0000, v110
	v_lshlrev_b32_e32 v110, 16, v111
	v_and_b32_e32 v111, 0xffff0000, v111
	s_waitcnt lgkmcnt(6)
	v_pk_fma_f32 v[4:5], v[124:125], v[4:5], 0 op_sel_hi:[1,1,0]
	v_pk_fma_f32 v[8:9], v[122:123], v[8:9], 0 op_sel_hi:[1,1,0]
	v_lshlrev_b32_e32 v140, 16, v117
	v_and_b32_e32 v141, 0xffff0000, v117
	v_pk_fma_f32 v[110:111], v[120:121], v[110:111], 0 op_sel_hi:[1,1,0]
	s_waitcnt lgkmcnt(4)
	v_pk_fma_f32 v[4:5], v[134:135], v[6:7], v[4:5]
	v_pk_fma_f32 v[6:7], v[132:133], v[10:11], v[8:9]
	v_pk_fma_f32 v[8:9], v[130:131], v[140:141], v[110:111]
	v_or_b32_e32 v197, 0x100, v194
	v_and_b32_e32 v47, 64, v191
	v_lshrrev_b32_e32 v198, 4, v197
	v_xor_b32_e32 v23, 1, v191
	v_add_u32_e32 v43, 64, v47
	v_cmp_lt_i32_e64 s[8:9], v23, v43
	v_mul_i32_i24_e32 v19, 0x10e00, v19
	v_add_u32_e32 v196, 0, v19
	v_cndmask_b32_e64 v23, v191, v23, s[8:9]
	v_lshlrev_b32_e32 v23, 2, v23
	v_mul_u32_u24_e32 v201, 0x110, v24
	v_or_b32_e32 v199, 0x200, v194
	v_lshrrev_b32_e32 v200, 4, v199
	v_mul_u32_u24_e32 v204, 0x110, v198
	v_or_b32_e32 v202, 0x300, v194
	v_lshrrev_b32_e32 v203, 4, v202
	v_mul_u32_u24_e32 v205, 0x110, v200
	v_mul_u32_u24_e32 v206, 0x110, v203
	s_waitcnt vmcnt(1)
	v_cndmask_b32_e64 v11, v15, 0, s[0:1]
	v_cndmask_b32_e64 v110, v13, 0, s[0:1]
	v_cndmask_b32_e64 v13, v14, 0, s[0:1]
	v_lshlrev_b32_e32 v10, 16, v11
	v_and_b32_e32 v11, 0xffff0000, v11
	v_cndmask_b32_e64 v117, v12, 0, s[0:1]
	v_lshlrev_b32_e32 v12, 16, v13
	v_and_b32_e32 v13, 0xffff0000, v13
	v_lshlrev_b32_e32 v14, 16, v110
	v_and_b32_e32 v15, 0xffff0000, v110
	s_waitcnt lgkmcnt(2)
	v_pk_fma_f32 v[4:5], v[150:151], v[10:11], v[4:5]
	s_waitcnt vmcnt(0)
	v_lshlrev_b32_e32 v10, 16, v3
	v_and_b32_e32 v11, 0xffff0000, v3
	v_pk_fma_f32 v[6:7], v[148:149], v[12:13], v[6:7]
	v_pk_fma_f32 v[8:9], v[146:147], v[14:15], v[8:9]
	v_lshlrev_b32_e32 v12, 16, v2
	v_and_b32_e32 v13, 0xffff0000, v2
	v_lshlrev_b32_e32 v2, 16, v1
	v_and_b32_e32 v3, 0xffff0000, v1
	s_waitcnt lgkmcnt(0)
	v_pk_fma_f32 v[4:5], v[158:159], v[10:11], v[4:5]
	v_pk_fma_f32 v[6:7], v[156:157], v[12:13], v[6:7]
	v_pk_fma_f32 v[110:111], v[154:155], v[2:3], v[8:9]
	v_mul_f32_e32 v1, 0xbfb8aa3b, v4
	v_mul_f32_e32 v2, 0xbfb8aa3b, v5
	v_mul_f32_e32 v3, 0xbfb8aa3b, v6
	v_exp_f32_e32 v1, v1
	v_exp_f32_e32 v2, v2
	v_exp_f32_e32 v3, v3
	v_mul_f32_e32 v9, 0xbfb8aa3b, v110
	v_exp_f32_e32 v11, v9
	v_add_f32_e32 v1, 1.0, v1
	v_add_f32_e32 v9, 1.0, v2
	v_add_f32_e32 v12, 1.0, v3
	v_rcp_f32_e32 v2, v1
	v_rcp_f32_e32 v3, v9
	v_mul_f32_e32 v8, 0xbfb8aa3b, v7
	v_exp_f32_e32 v8, v8
	v_mul_f32_e32 v10, 0xbfb8aa3b, v111
	v_pk_mul_f32 v[120:121], v[4:5], v[2:3]
	v_add_f32_e32 v2, 1.0, v11
	v_rcp_f32_e32 v130, v2
	v_lshlrev_b32_e32 v2, 16, v109
	v_and_b32_e32 v3, 0xffff0000, v109
	v_pk_fma_f32 v[2:3], v[118:119], v[2:3], 0 op_sel_hi:[1,1,0]
	v_lshlrev_b32_e32 v4, 16, v26
	v_and_b32_e32 v5, 0xffff0000, v26
	v_pk_fma_f32 v[2:3], v[128:129], v[4:5], v[2:3]
	v_lshlrev_b32_e32 v4, 16, v117
	v_and_b32_e32 v5, 0xffff0000, v117
	v_add_f32_e32 v1, 1.0, v8
	v_pk_fma_f32 v[2:3], v[144:145], v[4:5], v[2:3]
	v_lshlrev_b32_e32 v4, 16, v0
	v_and_b32_e32 v5, 0xffff0000, v0
	v_rcp_f32_e32 v9, v1
	v_exp_f32_e32 v1, v10
	v_pk_fma_f32 v[118:119], v[152:153], v[4:5], v[2:3]
	v_rcp_f32_e32 v8, v12
	v_mul_f32_e32 v0, 0xbfb8aa3b, v118
	v_exp_f32_e32 v26, v0
	v_add_u32_e32 v0, -3, v198
	v_add_u32_e32 v2, -2, v198
	v_or_b32_e32 v0, v36, v0
	v_or_b32_e32 v2, v36, v2
	v_add_u32_e32 v4, -1, v198
	v_add_f32_e32 v126, 1.0, v1
	v_mad_u64_u32 v[0:1], s[8:9], v0, s29, v[48:49]
	v_mad_u64_u32 v[2:3], s[8:9], v2, s29, v[48:49]
	v_or_b32_e32 v4, v36, v4
	v_add_u32_e32 v1, v112, v1
	v_add_u32_e32 v3, v112, v3
	v_mad_u64_u32 v[4:5], s[8:9], v4, s29, v[48:49]
	v_or_b32_e32 v12, v36, v198
	v_pk_mul_f32 v[124:125], v[6:7], v[8:9]
	global_load_dwordx4 v[8:11], v[0:1], off
	s_nop 0
	global_load_dwordx4 v[0:3], v[2:3], off
	v_add_u32_e32 v5, v112, v5
	v_mad_u64_u32 v[12:13], s[8:9], v12, s29, v[48:49]
	global_load_dwordx4 v[4:7], v[4:5], off
	v_add_u32_e32 v13, v112, v13
	global_load_dwordx4 v[12:15], v[12:13], off
	v_mul_f32_e32 v109, 0xbfb8aa3b, v119
	v_exp_f32_e32 v109, v109
	v_add_f32_e32 v26, 1.0, v26
	v_rcp_f32_e32 v128, v26
	v_rcp_f32_e32 v131, v126
	v_add_f32_e32 v26, 1.0, v109
	v_rcp_f32_e32 v129, v26
	v_pk_mul_f32 v[132:133], v[124:125], v[124:125]
	v_pk_mul_f32 v[130:131], v[110:111], v[130:131]
	v_pk_mul_f32 v[122:123], v[120:121], v[120:121]
	v_pk_mul_f32 v[118:119], v[118:119], v[128:129]
	v_pk_mul_f32 v[110:111], v[130:131], v[130:131]
	v_pk_mul_f32 v[128:129], v[118:119], v[118:119]
	v_xor_b32_e32 v109, 2, v191
	v_add_f32_e32 v26, v128, v129
	v_add_f32_e32 v26, v110, v26
	v_add_f32_e32 v26, v111, v26
	v_add_f32_e32 v26, v132, v26
	v_add_f32_e32 v26, v133, v26
	v_add_f32_e32 v26, v122, v26
	v_add_f32_e32 v26, v123, v26
	ds_bpermute_b32 v110, v23, v26
	v_cmp_lt_i32_e64 s[8:9], v109, v43
	s_waitcnt lgkmcnt(0)
	v_add_f32_e32 v26, v26, v110
	v_cndmask_b32_e64 v109, v191, v109, s[8:9]
	v_lshlrev_b32_e32 v109, 2, v109
	ds_bpermute_b32 v111, v109, v26
	v_xor_b32_e32 v110, 4, v191
	v_cmp_lt_i32_e64 s[8:9], v110, v43
	s_waitcnt lgkmcnt(0)
	v_add_f32_e32 v26, v26, v111
	v_cndmask_b32_e64 v110, v191, v110, s[8:9]
	v_lshlrev_b32_e32 v110, 2, v110
	ds_bpermute_b32 v117, v110, v26
	v_xor_b32_e32 v111, 8, v191
	v_cmp_lt_i32_e64 s[8:9], v111, v43
	s_waitcnt lgkmcnt(0)
	v_add_f32_e32 v26, v26, v117
	v_cndmask_b32_e64 v43, v191, v111, s[8:9]
	v_lshlrev_b32_e32 v111, 2, v43
	ds_bpermute_b32 v43, v111, v26
	s_waitcnt lgkmcnt(0)
	v_add_f32_e32 v26, v26, v43
	v_add_f32_e32 v26, 0x358637bd, v26
	v_mul_f32_e32 v43, 0x4b800000, v26
	v_cmp_gt_f32_e64 s[8:9], s70, v26
	s_waitcnt vmcnt(3)
	v_lshlrev_b32_e32 v140, 16, v11
	v_cndmask_b32_e64 v26, v26, v43, s[8:9]
	v_rsq_f32_e32 v26, v26
	v_and_b32_e32 v141, 0xffff0000, v11
	v_mul_f32_e32 v19, 0x45800000, v26
	v_cndmask_b32_e64 v19, v26, v19, s[8:9]
	v_mul_f32_e32 v26, 0x3db504f3, v19
	v_pk_mul_f32 v[118:119], v[118:119], v[26:27] op_sel_hi:[1,0]
	v_pk_mul_f32 v[122:123], v[130:131], v[26:27] op_sel_hi:[1,0]
	v_pk_mul_f32 v[124:125], v[124:125], v[26:27] op_sel_hi:[1,0]
	v_pk_mul_f32 v[128:129], v[120:121], v[26:27] op_sel_hi:[1,0]
	v_lshlrev_b32_e32 v26, 1, v25
	v_cvt_pk_bf16_f32 v118, v118, v119
	v_cvt_pk_bf16_f32 v119, v122, v123
	v_cvt_pk_bf16_f32 v120, v124, v125
	v_cvt_pk_bf16_f32 v121, v128, v129
	v_add3_u32 v117, v196, v201, v26
	ds_write_b128 v117, v[118:121] offset:4096
	ds_read_b128 v[118:121], v108 offset:16
	ds_read_b128 v[122:125], v108 offset:1040
	ds_read_b128 v[128:131], v108 offset:2064
	ds_read_b128 v[132:135], v108 offset:3088
	ds_read_b128 v[144:147], v108
	s_waitcnt lgkmcnt(4)
	v_pk_fma_f32 v[120:121], v[120:121], v[140:141], 0 op_sel_hi:[1,1,0]
	s_waitcnt vmcnt(2)
	v_lshlrev_b32_e32 v140, 16, v3
	v_and_b32_e32 v141, 0xffff0000, v3
	s_waitcnt lgkmcnt(3)
	v_pk_fma_f32 v[120:121], v[124:125], v[140:141], v[120:121]
	s_waitcnt vmcnt(1)
	v_lshlrev_b32_e32 v124, 16, v7
	v_and_b32_e32 v125, 0xffff0000, v7
	s_waitcnt lgkmcnt(2)
	v_pk_fma_f32 v[120:121], v[130:131], v[124:125], v[120:121]
	s_waitcnt vmcnt(0)
	v_lshlrev_b32_e32 v124, 16, v15
	v_and_b32_e32 v125, 0xffff0000, v15
	s_waitcnt lgkmcnt(1)
	v_pk_fma_f32 v[120:121], v[134:135], v[124:125], v[120:121]
	ds_read_b128 v[148:151], v108 offset:1024
	ds_read_b128 v[152:155], v108 offset:2048
	ds_read_b128 v[156:159], v108 offset:3072
	v_mul_f32_e32 v3, 0xbfb8aa3b, v120
	v_exp_f32_e32 v3, v3
	v_mul_f32_e32 v7, 0xbfb8aa3b, v121
	v_exp_f32_e32 v7, v7
	v_and_b32_e32 v15, 0xffff0000, v1
	v_add_f32_e32 v3, 1.0, v3
	v_rcp_f32_e32 v124, v3
	v_add_f32_e32 v3, 1.0, v7
	v_rcp_f32_e32 v125, v3
	v_and_b32_e32 v7, 0xffff0000, v14
	v_pk_mul_f32 v[120:121], v[120:121], v[124:125]
	v_lshlrev_b32_e32 v124, 16, v10
	v_and_b32_e32 v125, 0xffff0000, v10
	v_pk_fma_f32 v[10:11], v[118:119], v[124:125], 0 op_sel_hi:[1,1,0]
	v_lshlrev_b32_e32 v118, 16, v2
	v_and_b32_e32 v119, 0xffff0000, v2
	v_pk_fma_f32 v[2:3], v[122:123], v[118:119], v[10:11]
	v_lshlrev_b32_e32 v10, 16, v6
	v_and_b32_e32 v11, 0xffff0000, v6
	v_pk_fma_f32 v[2:3], v[128:129], v[10:11], v[2:3]
	v_lshlrev_b32_e32 v6, 16, v14
	v_pk_fma_f32 v[2:3], v[132:133], v[6:7], v[2:3]
	v_lshlrev_b32_e32 v10, 16, v9
	v_mul_f32_e32 v6, 0xbfb8aa3b, v2
	v_mul_f32_e32 v7, 0xbfb8aa3b, v3
	v_exp_f32_e32 v6, v6
	v_exp_f32_e32 v7, v7
	v_and_b32_e32 v11, 0xffff0000, v9
	s_waitcnt lgkmcnt(3)
	v_pk_fma_f32 v[10:11], v[146:147], v[10:11], 0 op_sel_hi:[1,1,0]
	v_lshlrev_b32_e32 v14, 16, v1
	s_waitcnt lgkmcnt(2)
	v_pk_fma_f32 v[10:11], v[150:151], v[14:15], v[10:11]
	v_lshlrev_b32_e32 v14, 16, v5
	v_and_b32_e32 v15, 0xffff0000, v5
	s_waitcnt lgkmcnt(1)
	v_pk_fma_f32 v[10:11], v[154:155], v[14:15], v[10:11]
	v_lshlrev_b32_e32 v14, 16, v13
	v_and_b32_e32 v15, 0xffff0000, v13
	v_add_f32_e32 v6, 1.0, v6
	v_add_f32_e32 v7, 1.0, v7
	s_waitcnt lgkmcnt(0)
	v_pk_fma_f32 v[122:123], v[158:159], v[14:15], v[10:11]
	v_rcp_f32_e32 v6, v6
	v_rcp_f32_e32 v7, v7
	v_mul_f32_e32 v1, 0xbfb8aa3b, v122
	v_exp_f32_e32 v1, v1
	v_mul_f32_e32 v5, 0xbfb8aa3b, v123
	v_pk_mul_f32 v[124:125], v[2:3], v[6:7]
	v_lshlrev_b32_e32 v2, 16, v8
	v_and_b32_e32 v3, 0xffff0000, v8
	v_add_f32_e32 v1, 1.0, v1
	v_pk_fma_f32 v[2:3], v[144:145], v[2:3], 0 op_sel_hi:[1,1,0]
	v_lshlrev_b32_e32 v6, 16, v0
	v_and_b32_e32 v7, 0xffff0000, v0
	v_rcp_f32_e32 v128, v1
	v_pk_fma_f32 v[0:1], v[148:149], v[6:7], v[2:3]
	v_lshlrev_b32_e32 v2, 16, v4
	v_and_b32_e32 v3, 0xffff0000, v4
	v_exp_f32_e32 v5, v5
	v_pk_fma_f32 v[0:1], v[152:153], v[2:3], v[0:1]
	v_lshlrev_b32_e32 v2, 16, v12
	v_and_b32_e32 v3, 0xffff0000, v12
	v_pk_fma_f32 v[130:131], v[156:157], v[2:3], v[0:1]
	v_add_u32_e32 v0, -3, v200
	v_add_u32_e32 v2, -2, v200
	v_or_b32_e32 v0, v36, v0
	v_or_b32_e32 v2, v36, v2
	v_add_u32_e32 v4, -1, v200
	v_mad_u64_u32 v[0:1], s[8:9], v0, s29, v[48:49]
	v_mad_u64_u32 v[2:3], s[8:9], v2, s29, v[48:49]
	v_or_b32_e32 v4, v36, v4
	v_add_f32_e32 v19, 1.0, v5
	v_add_u32_e32 v1, v112, v1
	v_add_u32_e32 v3, v112, v3
	v_mad_u64_u32 v[4:5], s[8:9], v4, s29, v[48:49]
	v_or_b32_e32 v12, v36, v200
	global_load_dwordx4 v[8:11], v[0:1], off
	s_nop 0
	global_load_dwordx4 v[0:3], v[2:3], off
	v_add_u32_e32 v5, v112, v5
	v_mad_u64_u32 v[12:13], s[8:9], v12, s29, v[48:49]
	global_load_dwordx4 v[4:7], v[4:5], off
	v_add_u32_e32 v13, v112, v13
	global_load_dwordx4 v[12:15], v[12:13], off
	v_mul_f32_e32 v25, 0xbfb8aa3b, v130
	v_exp_f32_e32 v25, v25
	v_mul_f32_e32 v43, 0xbfb8aa3b, v131
	v_exp_f32_e32 v43, v43
	v_rcp_f32_e32 v129, v19
	v_add_f32_e32 v19, 1.0, v25
	v_rcp_f32_e32 v132, v19
	v_add_f32_e32 v19, 1.0, v43
	v_rcp_f32_e32 v133, v19
	v_pk_mul_f32 v[122:123], v[122:123], v[128:129]
	v_pk_mul_f32 v[134:135], v[124:125], v[124:125]
	v_pk_mul_f32 v[128:129], v[122:123], v[122:123]
	v_pk_mul_f32 v[130:131], v[130:131], v[132:133]
	v_pk_mul_f32 v[118:119], v[120:121], v[120:121]
	v_pk_mul_f32 v[132:133], v[130:131], v[130:131]
	s_waitcnt vmcnt(3)
	v_lshlrev_b32_e32 v140, 16, v11
	v_add_f32_e32 v19, v132, v133
	v_add_f32_e32 v19, v128, v19
	v_add_f32_e32 v19, v129, v19
	v_add_f32_e32 v19, v134, v19
	v_add_f32_e32 v19, v135, v19
	v_add_f32_e32 v19, v118, v19
	v_add_f32_e32 v19, v119, v19
	ds_bpermute_b32 v25, v23, v19
	v_and_b32_e32 v141, 0xffff0000, v11
	s_waitcnt lgkmcnt(0)
	v_add_f32_e32 v19, v19, v25
	ds_bpermute_b32 v25, v109, v19
	s_waitcnt lgkmcnt(0)
	v_add_f32_e32 v19, v19, v25
	ds_bpermute_b32 v25, v110, v19
	s_waitcnt lgkmcnt(0)
	v_add_f32_e32 v19, v19, v25
	ds_bpermute_b32 v25, v111, v19
	s_waitcnt lgkmcnt(0)
	v_add_f32_e32 v19, v19, v25
	v_add_f32_e32 v19, 0x358637bd, v19
	v_mul_f32_e32 v25, 0x4b800000, v19
	v_cmp_gt_f32_e64 s[8:9], s70, v19
	s_nop 1
	v_cndmask_b32_e64 v19, v19, v25, s[8:9]
	v_rsq_f32_e32 v19, v19
	s_nop 0
	v_mul_f32_e32 v25, 0x45800000, v19
	v_cndmask_b32_e64 v19, v19, v25, s[8:9]
	v_mul_f32_e32 v118, 0x3db504f3, v19
	v_pk_mul_f32 v[128:129], v[130:131], v[118:119] op_sel_hi:[1,0]
	v_pk_mul_f32 v[122:123], v[122:123], v[118:119] op_sel_hi:[1,0]
	v_pk_mul_f32 v[124:125], v[124:125], v[118:119] op_sel_hi:[1,0]
	v_pk_mul_f32 v[130:131], v[120:121], v[118:119] op_sel_hi:[1,0]
	v_cvt_pk_bf16_f32 v118, v128, v129
	v_cvt_pk_bf16_f32 v119, v122, v123
	v_cvt_pk_bf16_f32 v120, v124, v125
	v_cvt_pk_bf16_f32 v121, v130, v131
	v_add3_u32 v19, v196, v204, v26
	ds_write_b128 v19, v[118:121] offset:4096
	ds_read_b128 v[118:121], v108 offset:16
	ds_read_b128 v[122:125], v108 offset:1040
	ds_read_b128 v[128:131], v108 offset:2064
	ds_read_b128 v[132:135], v108 offset:3088
	ds_read_b128 v[144:147], v108
	s_waitcnt lgkmcnt(4)
	v_pk_fma_f32 v[120:121], v[120:121], v[140:141], 0 op_sel_hi:[1,1,0]
	s_waitcnt vmcnt(2)
	v_lshlrev_b32_e32 v140, 16, v3
	v_and_b32_e32 v141, 0xffff0000, v3
	s_waitcnt lgkmcnt(3)
	v_pk_fma_f32 v[120:121], v[124:125], v[140:141], v[120:121]
	s_waitcnt vmcnt(1)
	v_lshlrev_b32_e32 v124, 16, v7
	v_and_b32_e32 v125, 0xffff0000, v7
	s_waitcnt lgkmcnt(2)
	v_pk_fma_f32 v[120:121], v[130:131], v[124:125], v[120:121]
	s_waitcnt vmcnt(0)
	v_lshlrev_b32_e32 v124, 16, v15
	v_and_b32_e32 v125, 0xffff0000, v15
	s_waitcnt lgkmcnt(1)
	v_pk_fma_f32 v[120:121], v[134:135], v[124:125], v[120:121]
	ds_read_b128 v[148:151], v108 offset:1024
	ds_read_b128 v[152:155], v108 offset:2048
	ds_read_b128 v[156:159], v108 offset:3072
	v_mul_f32_e32 v3, 0xbfb8aa3b, v120
	v_exp_f32_e32 v3, v3
	v_mul_f32_e32 v7, 0xbfb8aa3b, v121
	v_exp_f32_e32 v7, v7
	v_and_b32_e32 v15, 0xffff0000, v1
	v_add_f32_e32 v3, 1.0, v3
	v_rcp_f32_e32 v124, v3
	v_add_f32_e32 v3, 1.0, v7
	v_rcp_f32_e32 v125, v3
	v_and_b32_e32 v7, 0xffff0000, v14
	v_pk_mul_f32 v[120:121], v[120:121], v[124:125]
	v_lshlrev_b32_e32 v124, 16, v10
	v_and_b32_e32 v125, 0xffff0000, v10
	v_pk_fma_f32 v[10:11], v[118:119], v[124:125], 0 op_sel_hi:[1,1,0]
	v_lshlrev_b32_e32 v118, 16, v2
	v_and_b32_e32 v119, 0xffff0000, v2
	v_pk_fma_f32 v[2:3], v[122:123], v[118:119], v[10:11]
	v_lshlrev_b32_e32 v10, 16, v6
	v_and_b32_e32 v11, 0xffff0000, v6
	v_pk_fma_f32 v[2:3], v[128:129], v[10:11], v[2:3]
	v_lshlrev_b32_e32 v6, 16, v14
	v_pk_fma_f32 v[2:3], v[132:133], v[6:7], v[2:3]
	v_lshlrev_b32_e32 v10, 16, v9
	v_mul_f32_e32 v6, 0xbfb8aa3b, v2
	v_mul_f32_e32 v7, 0xbfb8aa3b, v3
	v_exp_f32_e32 v6, v6
	v_exp_f32_e32 v7, v7
	v_and_b32_e32 v11, 0xffff0000, v9
	s_waitcnt lgkmcnt(3)
	v_pk_fma_f32 v[10:11], v[146:147], v[10:11], 0 op_sel_hi:[1,1,0]
	v_lshlrev_b32_e32 v14, 16, v1
	s_waitcnt lgkmcnt(2)
	v_pk_fma_f32 v[10:11], v[150:151], v[14:15], v[10:11]
	v_lshlrev_b32_e32 v14, 16, v5
	v_and_b32_e32 v15, 0xffff0000, v5
	s_waitcnt lgkmcnt(1)
	v_pk_fma_f32 v[10:11], v[154:155], v[14:15], v[10:11]
	v_lshlrev_b32_e32 v14, 16, v13
	v_and_b32_e32 v15, 0xffff0000, v13
	v_add_f32_e32 v6, 1.0, v6
	v_add_f32_e32 v7, 1.0, v7
	s_waitcnt lgkmcnt(0)
	v_pk_fma_f32 v[122:123], v[158:159], v[14:15], v[10:11]
	v_rcp_f32_e32 v6, v6
	v_rcp_f32_e32 v7, v7
	v_mul_f32_e32 v1, 0xbfb8aa3b, v122
	v_exp_f32_e32 v1, v1
	v_mul_f32_e32 v5, 0xbfb8aa3b, v123
	v_pk_mul_f32 v[124:125], v[2:3], v[6:7]
	v_lshlrev_b32_e32 v2, 16, v8
	v_and_b32_e32 v3, 0xffff0000, v8
	v_add_f32_e32 v1, 1.0, v1
	v_pk_fma_f32 v[2:3], v[144:145], v[2:3], 0 op_sel_hi:[1,1,0]
	v_lshlrev_b32_e32 v6, 16, v0
	v_and_b32_e32 v7, 0xffff0000, v0
	v_rcp_f32_e32 v128, v1
	v_pk_fma_f32 v[0:1], v[148:149], v[6:7], v[2:3]
	v_lshlrev_b32_e32 v2, 16, v4
	v_and_b32_e32 v3, 0xffff0000, v4
	v_exp_f32_e32 v5, v5
	v_pk_fma_f32 v[0:1], v[152:153], v[2:3], v[0:1]
	v_lshlrev_b32_e32 v2, 16, v12
	v_and_b32_e32 v3, 0xffff0000, v12
	v_pk_fma_f32 v[130:131], v[156:157], v[2:3], v[0:1]
	v_add_u32_e32 v0, -3, v203
	v_add_u32_e32 v2, -2, v203
	v_or_b32_e32 v0, v36, v0
	v_or_b32_e32 v2, v36, v2
	v_add_u32_e32 v4, -1, v203
	v_mad_u64_u32 v[0:1], s[8:9], v0, s29, v[48:49]
	v_mad_u64_u32 v[2:3], s[8:9], v2, s29, v[48:49]
	v_or_b32_e32 v4, v36, v4
	v_add_f32_e32 v19, 1.0, v5
	v_add_u32_e32 v1, v112, v1
	v_add_u32_e32 v3, v112, v3
	v_mad_u64_u32 v[4:5], s[8:9], v4, s29, v[48:49]
	v_or_b32_e32 v12, v36, v203
	global_load_dwordx4 v[8:11], v[0:1], off
	s_nop 0
	global_load_dwordx4 v[0:3], v[2:3], off
	v_add_u32_e32 v5, v112, v5
	v_mad_u64_u32 v[12:13], s[8:9], v12, s29, v[48:49]
	global_load_dwordx4 v[4:7], v[4:5], off
	v_add_u32_e32 v13, v112, v13
	global_load_dwordx4 v[12:15], v[12:13], off
	v_mul_f32_e32 v25, 0xbfb8aa3b, v130
	v_exp_f32_e32 v25, v25
	v_mul_f32_e32 v43, 0xbfb8aa3b, v131
	v_exp_f32_e32 v43, v43
	v_rcp_f32_e32 v129, v19
	v_add_f32_e32 v19, 1.0, v25
	v_rcp_f32_e32 v48, v19
	v_add_f32_e32 v19, 1.0, v43
	v_rcp_f32_e32 v49, v19
	v_pk_mul_f32 v[122:123], v[122:123], v[128:129]
	v_pk_mul_f32 v[132:133], v[124:125], v[124:125]
	v_pk_mul_f32 v[128:129], v[122:123], v[122:123]
	v_pk_mul_f32 v[48:49], v[130:131], v[48:49]
	v_pk_mul_f32 v[118:119], v[120:121], v[120:121]
	v_pk_mul_f32 v[130:131], v[48:49], v[48:49]
	s_nop 0
	v_add_f32_e32 v19, v130, v131
	v_add_f32_e32 v19, v128, v19
	v_add_f32_e32 v19, v129, v19
	v_add_f32_e32 v19, v132, v19
	v_add_f32_e32 v19, v133, v19
	v_add_f32_e32 v19, v118, v19
	v_add_f32_e32 v19, v119, v19
	ds_bpermute_b32 v25, v23, v19
	s_waitcnt lgkmcnt(0)
	v_add_f32_e32 v19, v19, v25
	ds_bpermute_b32 v25, v109, v19
	s_waitcnt lgkmcnt(0)
	v_add_f32_e32 v19, v19, v25
	ds_bpermute_b32 v25, v110, v19
	s_waitcnt lgkmcnt(0)
	v_add_f32_e32 v19, v19, v25
	ds_bpermute_b32 v25, v111, v19
	s_waitcnt lgkmcnt(0)
	v_add_f32_e32 v19, v19, v25
	v_add_f32_e32 v19, 0x358637bd, v19
	v_mul_f32_e32 v25, 0x4b800000, v19
	v_cmp_gt_f32_e64 s[8:9], s70, v19
	s_nop 1
	v_cndmask_b32_e64 v19, v19, v25, s[8:9]
	v_rsq_f32_e32 v19, v19
	s_nop 0
	v_mul_f32_e32 v25, 0x45800000, v19
	v_cndmask_b32_e64 v19, v19, v25, s[8:9]
	v_mul_f32_e32 v118, 0x3db504f3, v19
	v_pk_mul_f32 v[48:49], v[48:49], v[118:119] op_sel_hi:[1,0]
	v_pk_mul_f32 v[122:123], v[122:123], v[118:119] op_sel_hi:[1,0]
	v_pk_mul_f32 v[124:125], v[124:125], v[118:119] op_sel_hi:[1,0]
	v_pk_mul_f32 v[128:129], v[120:121], v[118:119] op_sel_hi:[1,0]
	v_cvt_pk_bf16_f32 v118, v48, v49
	v_cvt_pk_bf16_f32 v119, v122, v123
	v_cvt_pk_bf16_f32 v120, v124, v125
	v_cvt_pk_bf16_f32 v121, v128, v129
	v_add3_u32 v19, v196, v205, v26
	ds_write_b128 v19, v[118:121] offset:4096
	ds_read_b128 v[118:121], v108 offset:16
	ds_read_b128 v[122:125], v108 offset:1040
	ds_read_b128 v[128:131], v108 offset:2064
	ds_read_b128 v[132:135], v108 offset:3088
	ds_read_b128 v[144:147], v108
	s_waitcnt vmcnt(3)
	v_lshlrev_b32_e32 v48, 16, v11
	v_and_b32_e32 v49, 0xffff0000, v11
	s_waitcnt lgkmcnt(4)
	v_pk_fma_f32 v[48:49], v[120:121], v[48:49], 0 op_sel_hi:[1,1,0]
	s_waitcnt vmcnt(2)
	v_lshlrev_b32_e32 v120, 16, v3
	v_and_b32_e32 v121, 0xffff0000, v3
	s_waitcnt lgkmcnt(3)
	v_pk_fma_f32 v[48:49], v[124:125], v[120:121], v[48:49]
	s_waitcnt vmcnt(1)
	v_lshlrev_b32_e32 v120, 16, v7
	v_and_b32_e32 v121, 0xffff0000, v7
	s_waitcnt lgkmcnt(2)
	v_pk_fma_f32 v[48:49], v[130:131], v[120:121], v[48:49]
	s_waitcnt vmcnt(0)
	v_lshlrev_b32_e32 v120, 16, v15
	v_and_b32_e32 v121, 0xffff0000, v15
	s_waitcnt lgkmcnt(1)
	v_pk_fma_f32 v[48:49], v[134:135], v[120:121], v[48:49]
	ds_read_b128 v[148:151], v108 offset:1024
	ds_read_b128 v[152:155], v108 offset:2048
	ds_read_b128 v[156:159], v108 offset:3072
	v_mul_f32_e32 v3, 0xbfb8aa3b, v48
	v_exp_f32_e32 v3, v3
	v_mul_f32_e32 v7, 0xbfb8aa3b, v49
	v_exp_f32_e32 v7, v7
	v_and_b32_e32 v15, 0xffff0000, v9
	v_add_f32_e32 v3, 1.0, v3
	v_rcp_f32_e32 v120, v3
	v_add_f32_e32 v3, 1.0, v7
	v_rcp_f32_e32 v121, v3
	v_and_b32_e32 v7, 0xffff0000, v14
	v_mov_b32_e32 v25, v21
	v_pk_mul_f32 v[48:49], v[48:49], v[120:121]
	v_lshlrev_b32_e32 v120, 16, v10
	v_and_b32_e32 v121, 0xffff0000, v10
	v_pk_fma_f32 v[10:11], v[118:119], v[120:121], 0 op_sel_hi:[1,1,0]
	v_lshlrev_b32_e32 v118, 16, v2
	v_and_b32_e32 v119, 0xffff0000, v2
	v_pk_fma_f32 v[2:3], v[122:123], v[118:119], v[10:11]
	v_lshlrev_b32_e32 v10, 16, v6
	v_and_b32_e32 v11, 0xffff0000, v6
	v_pk_fma_f32 v[2:3], v[128:129], v[10:11], v[2:3]
	v_lshlrev_b32_e32 v6, 16, v14
	v_pk_fma_f32 v[2:3], v[132:133], v[6:7], v[2:3]
	v_lshlrev_b32_e32 v14, 16, v9
	v_mul_f32_e32 v6, 0xbfb8aa3b, v2
	v_exp_f32_e32 v10, v6
	v_mul_f32_e32 v6, 0xbfb8aa3b, v3
	s_waitcnt lgkmcnt(3)
	v_pk_fma_f32 v[14:15], v[146:147], v[14:15], 0 op_sel_hi:[1,1,0]
	v_lshlrev_b32_e32 v118, 16, v1
	v_and_b32_e32 v119, 0xffff0000, v1
	v_exp_f32_e32 v11, v6
	s_waitcnt lgkmcnt(2)
	v_pk_fma_f32 v[14:15], v[150:151], v[118:119], v[14:15]
	v_lshlrev_b32_e32 v118, 16, v5
	v_and_b32_e32 v119, 0xffff0000, v5
	s_waitcnt lgkmcnt(1)
	v_pk_fma_f32 v[14:15], v[154:155], v[118:119], v[14:15]
	v_lshlrev_b32_e32 v118, 16, v13
	v_and_b32_e32 v119, 0xffff0000, v13
	s_waitcnt lgkmcnt(0)
	v_pk_fma_f32 v[14:15], v[158:159], v[118:119], v[14:15]
	v_add_f32_e32 v10, 1.0, v10
	v_mul_f32_e32 v1, 0xbfb8aa3b, v14
	v_add_f32_e32 v11, 1.0, v11
	v_exp_f32_e32 v1, v1
	v_rcp_f32_e32 v10, v10
	v_rcp_f32_e32 v11, v11
	v_mul_f32_e32 v5, 0xbfb8aa3b, v15
	v_exp_f32_e32 v5, v5
	v_lshlrev_b32_e32 v118, 16, v8
	v_and_b32_e32 v119, 0xffff0000, v8
	v_add_f32_e32 v1, 1.0, v1
	v_pk_fma_f32 v[8:9], v[144:145], v[118:119], 0 op_sel_hi:[1,1,0]
	v_lshlrev_b32_e32 v118, 16, v0
	v_and_b32_e32 v119, 0xffff0000, v0
	v_pk_mul_f32 v[2:3], v[2:3], v[10:11]
	v_rcp_f32_e32 v10, v1
	v_pk_fma_f32 v[0:1], v[148:149], v[118:119], v[8:9]
	v_lshlrev_b32_e32 v8, 16, v4
	v_and_b32_e32 v9, 0xffff0000, v4
	v_add_f32_e32 v11, 1.0, v5
	v_pk_fma_f32 v[0:1], v[152:153], v[8:9], v[0:1]
	v_lshlrev_b32_e32 v4, 16, v12
	v_and_b32_e32 v5, 0xffff0000, v12
	v_pk_fma_f32 v[0:1], v[156:157], v[4:5], v[0:1]
	v_rcp_f32_e32 v11, v11
	v_mul_f32_e32 v4, 0xbfb8aa3b, v0
	v_mul_f32_e32 v5, 0xbfb8aa3b, v1
	v_exp_f32_e32 v4, v4
	v_exp_f32_e32 v5, v5
	v_pk_mul_f32 v[10:11], v[14:15], v[10:11]
	v_pk_mul_f32 v[8:9], v[2:3], v[2:3]
	v_add_f32_e32 v4, 1.0, v4
	v_add_f32_e32 v5, 1.0, v5
	v_rcp_f32_e32 v4, v4
	v_rcp_f32_e32 v5, v5
	v_pk_mul_f32 v[12:13], v[10:11], v[10:11]
	v_pk_mul_f32 v[6:7], v[48:49], v[48:49]
	v_pk_mul_f32 v[0:1], v[0:1], v[4:5]
	s_nop 0
	v_pk_mul_f32 v[4:5], v[0:1], v[0:1]
	s_nop 0
	v_add_f32_e32 v4, v4, v5
	v_add_f32_e32 v4, v12, v4
	v_add_f32_e32 v4, v13, v4
	v_add_f32_e32 v4, v8, v4
	v_add_f32_e32 v4, v9, v4
	v_add_f32_e32 v4, v6, v4
	v_add_f32_e32 v4, v7, v4
	ds_bpermute_b32 v5, v23, v4
	s_waitcnt lgkmcnt(0)
	v_add_f32_e32 v4, v4, v5
	ds_bpermute_b32 v5, v109, v4
	s_waitcnt lgkmcnt(0)
	v_add_f32_e32 v4, v4, v5
	ds_bpermute_b32 v5, v110, v4
	s_waitcnt lgkmcnt(0)
	v_add_f32_e32 v4, v4, v5
	ds_bpermute_b32 v5, v111, v4
	s_waitcnt lgkmcnt(0)
	v_add_f32_e32 v4, v4, v5
	v_add_f32_e32 v4, 0x358637bd, v4
	v_mul_f32_e32 v5, 0x4b800000, v4
	v_cmp_gt_f32_e64 s[8:9], s70, v4
	s_nop 1
	v_cndmask_b32_e64 v4, v4, v5, s[8:9]
	v_rsq_f32_e32 v4, v4
	s_nop 0
	v_mul_f32_e32 v5, 0x45800000, v4
	v_cndmask_b32_e64 v4, v4, v5, s[8:9]
	v_mul_f32_e32 v4, 0x3db504f3, v4
	v_pk_mul_f32 v[0:1], v[0:1], v[4:5] op_sel_hi:[1,0]
	v_pk_mul_f32 v[6:7], v[10:11], v[4:5] op_sel_hi:[1,0]
	v_pk_mul_f32 v[2:3], v[2:3], v[4:5] op_sel_hi:[1,0]
	v_pk_mul_f32 v[4:5], v[48:49], v[4:5] op_sel_hi:[1,0]
	v_cvt_pk_bf16_f32 v0, v0, v1
	v_cvt_pk_bf16_f32 v1, v6, v7
	v_cvt_pk_bf16_f32 v2, v2, v3
	v_cvt_pk_bf16_f32 v3, v4, v5
	v_add3_u32 v4, v196, v206, v26
	ds_write_b128 v4, v[0:3] offset:4096
	v_mov_b64_e32 v[2:3], 0x20600000
	v_mov_b64_e32 v[0:1], 0x5000
	v_mov_b64_e32 v[4:5], v[24:25]
	s_and_saveexec_b64 s[8:9], vcc
	v_mov_b32_e32 v19, v21
	v_mov_b64_e32 v[2:3], 0x8100000
	v_mov_b64_e32 v[0:1], 0x6000
	v_mov_b64_e32 v[4:5], v[18:19]
	v_mov_b64_e32 v[16:17], v[36:37]
	s_or_b64 exec, exec, s[8:9]
	v_mad_u64_u32 v[6:7], s[8:9], v46, v114, 0
	v_add_u32_e32 v7, v7, v20
	v_lshl_or_b32 v20, v113, 1, v192
	v_lshl_add_u64 v[2:3], s[82:83], 0, v[2:3]
	v_lshl_add_u64 v[2:3], v[2:3], 0, v[20:21]
	v_lshl_add_u64 v[4:5], v[16:17], 0, v[4:5]
	v_mad_u64_u32 v[2:3], s[8:9], v4, v0, v[2:3]
	v_lshl_add_u64 v[10:11], s[14:15], 0, v[20:21]
	v_lshl_add_u64 v[12:13], s[68:69], 0, v[20:21]
	v_mov_b32_e32 v4, v3
	v_mad_u64_u32 v[0:1], s[8:9], v5, v0, v[4:5]
	v_cndmask_b32_e64 v5, v11, v13, s[4:5]
	v_cndmask_b32_e64 v4, v10, v12, s[4:5]
	v_mov_b32_e32 v3, v0
	v_lshl_add_u64 v[4:5], v[4:5], 0, v[6:7]
	global_load_dwordx4 v[0:3], v[2:3], off
	s_nop 0
	global_load_dwordx4 v[4:7], v[4:5], off
	s_and_saveexec_b64 s[4:5], s[6:7]
	s_xor_b64 s[4:5], exec, s[4:5]
	v_mov_b32_e32 v43, v21
	v_lshl_add_u64 v[10:11], v[36:37], 0, v[42:43]
	v_mad_u64_u32 v[8:9], s[6:7], v10, s29, v[12:13]
	v_mov_b32_e32 v10, v9
	v_mad_u64_u32 v[10:11], s[6:7], v11, s29, v[10:11]
	v_mov_b32_e32 v9, v10
	s_andn2_saveexec_b64 s[4:5], s[4:5]
	v_lshl_add_u64 v[8:9], v[10:11], 0, v[44:45]
	s_mov_b64 s[6:7], 0xa000
	v_lshl_add_u64 v[8:9], v[8:9], 0, s[6:7]
	s_or_b64 exec, exec, s[4:5]
	global_load_dwordx4 v[8:11], v[8:9], off
	v_mad_u64_u32 v[14:15], s[4:5], v115, s29, 0
	v_add_u32_e32 v15, v15, v112
	v_lshl_add_u64 v[14:15], v[12:13], 0, v[14:15]
	global_load_dwordx4 v[14:17], v[14:15], off
	s_waitcnt vmcnt(2)
	v_cndmask_b32_e64 v113, v4, 0, s[24:25]
	v_cndmask_b32_e64 v114, v5, 0, s[24:25]
	v_cndmask_b32_e64 v115, v6, 0, s[24:25]
	v_cndmask_b32_e64 v126, v7, 0, s[24:25]
	v_cndmask_b32_e64 v140, v0, 0, s[10:11]
	v_cndmask_b32_e64 v141, v1, 0, s[10:11]
	v_cndmask_b32_e64 v144, v2, 0, s[10:11]
	v_cndmask_b32_e64 v19, v3, 0, s[10:11]
	v_lshlrev_b32_e32 v18, 16, v19
	v_and_b32_e32 v19, 0xffff0000, v19
	v_bfe_u32 v20, v38, 6, 2
	s_waitcnt vmcnt(1)
	v_cndmask_b32_e64 v25, v8, 0, s[0:1]
	v_cndmask_b32_e64 v46, v9, 0, s[0:1]
	v_cndmask_b32_e64 v48, v10, 0, s[0:1]
	v_cndmask_b32_e64 v49, v11, 0, s[0:1]
	ds_read_b128 v[0:3], v108 offset:512
	ds_read_b128 v[4:7], v108 offset:528
	ds_read_b128 v[8:11], v108 offset:1536
	ds_read_b128 v[42:45], v108 offset:1552
	ds_read_b128 v[118:121], v108 offset:2560
	ds_read_b128 v[122:125], v108 offset:2576
	ds_read_b128 v[128:131], v108 offset:3584
	ds_read_b128 v[132:135], v108 offset:3600
	s_waitcnt lgkmcnt(6)
	v_pk_fma_f32 v[6:7], v[6:7], v[18:19], 0 op_sel_hi:[1,1,0]
	v_lshlrev_b32_e32 v18, 16, v126
	v_and_b32_e32 v19, 0xffff0000, v126
	s_waitcnt lgkmcnt(4)
	v_pk_fma_f32 v[6:7], v[44:45], v[18:19], v[6:7]
	v_lshlrev_b32_e32 v18, 16, v49
	v_and_b32_e32 v19, 0xffff0000, v49
	s_waitcnt lgkmcnt(2)
	v_pk_fma_f32 v[6:7], v[124:125], v[18:19], v[6:7]
	s_waitcnt vmcnt(0)
	v_lshlrev_b32_e32 v18, 16, v17
	v_and_b32_e32 v19, 0xffff0000, v17
	v_lshlrev_b32_e32 v44, 16, v144
	v_and_b32_e32 v45, 0xffff0000, v144
	s_waitcnt lgkmcnt(0)
	v_pk_fma_f32 v[6:7], v[134:135], v[18:19], v[6:7]
	v_pk_fma_f32 v[4:5], v[4:5], v[44:45], 0 op_sel_hi:[1,1,0]
	v_lshlrev_b32_e32 v44, 16, v115
	v_and_b32_e32 v45, 0xffff0000, v115
	v_mul_f32_e32 v17, 0xbfb8aa3b, v6
	v_pk_fma_f32 v[4:5], v[42:43], v[44:45], v[4:5]
	v_lshlrev_b32_e32 v42, 16, v48
	v_and_b32_e32 v43, 0xffff0000, v48
	v_exp_f32_e32 v17, v17
	v_pk_fma_f32 v[4:5], v[122:123], v[42:43], v[4:5]
	v_lshlrev_b32_e32 v42, 16, v16
	v_and_b32_e32 v43, 0xffff0000, v16
	v_pk_fma_f32 v[4:5], v[132:133], v[42:43], v[4:5]
	v_lshlrev_b32_e32 v42, 16, v141
	v_and_b32_e32 v43, 0xffff0000, v141
	v_pk_fma_f32 v[2:3], v[2:3], v[42:43], 0 op_sel_hi:[1,1,0]
	v_lshlrev_b32_e32 v42, 16, v114
	v_and_b32_e32 v43, 0xffff0000, v114
	v_pk_fma_f32 v[2:3], v[10:11], v[42:43], v[2:3]
	v_lshlrev_b32_e32 v42, 16, v140
	v_and_b32_e32 v43, 0xffff0000, v140
	v_add_f32_e32 v17, 1.0, v17
	v_pk_fma_f32 v[0:1], v[0:1], v[42:43], 0 op_sel_hi:[1,1,0]
	v_lshlrev_b32_e32 v42, 16, v113
	v_and_b32_e32 v43, 0xffff0000, v113
	v_rcp_f32_e32 v18, v17
	v_mul_f32_e32 v17, 0xbfb8aa3b, v7
	v_pk_fma_f32 v[0:1], v[8:9], v[42:43], v[0:1]
	v_lshlrev_b32_e32 v8, 16, v25
	v_and_b32_e32 v9, 0xffff0000, v25
	v_exp_f32_e32 v17, v17
	v_lshlrev_b32_e32 v10, 16, v46
	v_and_b32_e32 v11, 0xffff0000, v46
	v_pk_fma_f32 v[0:1], v[118:119], v[8:9], v[0:1]
	v_lshlrev_b32_e32 v8, 16, v14
	v_and_b32_e32 v9, 0xffff0000, v14
	v_pk_fma_f32 v[2:3], v[120:121], v[10:11], v[2:3]
	v_lshlrev_b32_e32 v10, 16, v15
	v_and_b32_e32 v11, 0xffff0000, v15
	v_pk_fma_f32 v[0:1], v[128:129], v[8:9], v[0:1]
	v_pk_fma_f32 v[2:3], v[130:131], v[10:11], v[2:3]
	v_mul_f32_e32 v8, 0xbfb8aa3b, v0
	v_mul_f32_e32 v9, 0xbfb8aa3b, v1
	v_mul_f32_e32 v10, 0xbfb8aa3b, v2
	v_mul_f32_e32 v11, 0xbfb8aa3b, v3
	v_exp_f32_e32 v8, v8
	v_exp_f32_e32 v9, v9
	v_add_f32_e32 v17, 1.0, v17
	v_exp_f32_e32 v10, v10
	v_exp_f32_e32 v11, v11
	v_rcp_f32_e32 v19, v17
	v_mul_f32_e32 v16, 0xbfb8aa3b, v4
	v_mul_f32_e32 v17, 0xbfb8aa3b, v5
	v_exp_f32_e32 v16, v16
	v_exp_f32_e32 v17, v17
	v_add_f32_e32 v8, 1.0, v8
	v_add_f32_e32 v9, 1.0, v9
	v_add_f32_e32 v10, 1.0, v10
	v_add_f32_e32 v11, 1.0, v11
	v_rcp_f32_e32 v8, v8
	v_rcp_f32_e32 v9, v9
	v_rcp_f32_e32 v10, v10
	v_rcp_f32_e32 v11, v11
	v_add_f32_e32 v16, 1.0, v16
	v_add_f32_e32 v17, 1.0, v17
	v_rcp_f32_e32 v16, v16
	v_rcp_f32_e32 v17, v17
	v_pk_mul_f32 v[0:1], v[0:1], v[8:9]
	v_pk_mul_f32 v[2:3], v[2:3], v[10:11]
	v_pk_mul_f32 v[8:9], v[0:1], v[0:1]
	v_pk_mul_f32 v[10:11], v[2:3], v[2:3]
	v_add_f32_e32 v8, v8, v9
	v_pk_mul_f32 v[4:5], v[4:5], v[16:17]
	v_add_f32_e32 v8, v10, v8
	v_pk_mul_f32 v[16:17], v[4:5], v[4:5]
	v_add_f32_e32 v8, v11, v8
	v_pk_mul_f32 v[6:7], v[6:7], v[18:19]
	v_add_f32_e32 v8, v16, v8
	v_pk_mul_f32 v[18:19], v[6:7], v[6:7]
	v_add_f32_e32 v8, v17, v8
	v_add_f32_e32 v8, v18, v8
	v_add_f32_e32 v8, v19, v8
	ds_bpermute_b32 v9, v23, v8
	v_or_b32_e32 v25, 16, v24
	v_or_b32_e32 v14, v36, v25
	v_mad_u64_u32 v[14:15], s[0:1], v14, s29, v[12:13]
	s_waitcnt lgkmcnt(0)
	v_add_f32_e32 v8, v8, v9
	ds_bpermute_b32 v9, v109, v8
	v_add_u32_e32 v15, v112, v15
	global_load_dwordx4 v[14:17], v[14:15], off
	s_waitcnt lgkmcnt(0)
	v_add_f32_e32 v8, v8, v9
	ds_bpermute_b32 v9, v110, v8
	s_waitcnt lgkmcnt(0)
	v_add_f32_e32 v8, v8, v9
	ds_bpermute_b32 v9, v111, v8
	s_waitcnt lgkmcnt(0)
	v_add_f32_e32 v8, v8, v9
	v_add_f32_e32 v8, 0x358637bd, v8
	v_cmp_gt_f32_e32 vcc, s70, v8
	v_mul_f32_e32 v9, 0x4b800000, v8
	s_nop 0
	v_cndmask_b32_e32 v8, v8, v9, vcc
	v_rsq_f32_e32 v8, v8
	s_nop 0
	v_mul_f32_e32 v9, 0x45800000, v8
	v_cndmask_b32_e32 v8, v8, v9, vcc
	v_pk_mul_f32 v[0:1], v[0:1], v[8:9] op_sel_hi:[1,0]
	v_pk_mul_f32 v[2:3], v[2:3], v[8:9] op_sel_hi:[1,0]
	v_pk_mul_f32 v[4:5], v[4:5], v[8:9] op_sel_hi:[1,0]
	v_pk_mul_f32 v[6:7], v[6:7], v[8:9] op_sel_hi:[1,0]
	v_cvt_pk_bf16_f32 v0, v0, v1
	v_cvt_pk_bf16_f32 v1, v2, v3
	v_cvt_pk_bf16_f32 v2, v4, v5
	v_cvt_pk_bf16_f32 v3, v6, v7
	ds_write_b128 v117, v[0:3] offset:21504
	v_add_u32_e32 v0, 13, v24
	v_or_b32_e32 v0, v36, v0
	v_add_u32_e32 v4, 14, v24
	v_mad_u64_u32 v[0:1], s[0:1], v0, s29, v[12:13]
	v_or_b32_e32 v4, v36, v4
	v_add_u32_e32 v8, 15, v24
	v_add_u32_e32 v1, v112, v1
	v_mad_u64_u32 v[4:5], s[0:1], v4, s29, v[12:13]
	v_or_b32_e32 v8, v36, v8
	global_load_dwordx4 v[0:3], v[0:1], off
	v_add_u32_e32 v5, v112, v5
	v_mad_u64_u32 v[8:9], s[0:1], v8, s29, v[12:13]
	global_load_dwordx4 v[4:7], v[4:5], off
	v_add_u32_e32 v9, v112, v9
	global_load_dwordx4 v[8:11], v[8:9], off
	ds_read_b128 v[42:45], v108 offset:512
	ds_read_b128 v[118:121], v108 offset:528
	ds_read_b128 v[122:125], v108 offset:1536
	ds_read_b128 v[128:131], v108 offset:1552
	ds_read_b128 v[132:135], v108 offset:2560
	ds_read_b128 v[144:147], v108 offset:2576
	ds_read_b128 v[148:151], v108 offset:3584
	ds_read_b128 v[152:155], v108 offset:3600
	s_waitcnt vmcnt(2)
	v_lshlrev_b32_e32 v18, 16, v3
	v_and_b32_e32 v19, 0xffff0000, v3
	s_waitcnt lgkmcnt(6)
	v_pk_fma_f32 v[18:19], v[120:121], v[18:19], 0 op_sel_hi:[1,1,0]
	v_lshlrev_b32_e32 v114, 16, v2
	s_waitcnt vmcnt(1)
	v_lshlrev_b32_e32 v48, 16, v7
	v_and_b32_e32 v49, 0xffff0000, v7
	s_waitcnt lgkmcnt(4)
	v_pk_fma_f32 v[18:19], v[130:131], v[48:49], v[18:19]
	s_waitcnt vmcnt(0)
	v_lshlrev_b32_e32 v48, 16, v11
	v_and_b32_e32 v49, 0xffff0000, v11
	s_waitcnt lgkmcnt(2)
	v_pk_fma_f32 v[18:19], v[146:147], v[48:49], v[18:19]
	v_lshlrev_b32_e32 v48, 16, v17
	v_and_b32_e32 v49, 0xffff0000, v17
	s_waitcnt lgkmcnt(0)
	v_pk_fma_f32 v[18:19], v[154:155], v[48:49], v[18:19]
	v_and_b32_e32 v115, 0xffff0000, v2
	v_mul_f32_e32 v3, 0xbfb8aa3b, v18
	v_exp_f32_e32 v3, v3
	v_and_b32_e32 v7, 0xffff0000, v10
	v_and_b32_e32 v11, 0xffff0000, v1
	v_and_b32_e32 v17, 0xffff0000, v5
	v_add_f32_e32 v3, 1.0, v3
	v_rcp_f32_e32 v48, v3
	v_mul_f32_e32 v3, 0xbfb8aa3b, v19
	v_exp_f32_e32 v3, v3
	s_nop 0
	v_add_f32_e32 v3, 1.0, v3
	v_rcp_f32_e32 v49, v3
	v_pk_fma_f32 v[2:3], v[118:119], v[114:115], 0 op_sel_hi:[1,1,0]
	v_lshlrev_b32_e32 v114, 16, v6
	v_and_b32_e32 v115, 0xffff0000, v6
	v_pk_fma_f32 v[2:3], v[128:129], v[114:115], v[2:3]
	v_lshlrev_b32_e32 v6, 16, v10
	v_lshlrev_b32_e32 v10, 16, v1
	v_pk_fma_f32 v[2:3], v[144:145], v[6:7], v[2:3]
	v_lshlrev_b32_e32 v6, 16, v16
	v_and_b32_e32 v7, 0xffff0000, v16
	v_pk_fma_f32 v[10:11], v[44:45], v[10:11], 0 op_sel_hi:[1,1,0]
	v_lshlrev_b32_e32 v16, 16, v5
	v_pk_fma_f32 v[10:11], v[124:125], v[16:17], v[10:11]
	v_lshlrev_b32_e32 v16, 16, v9
	v_and_b32_e32 v17, 0xffff0000, v9
	v_pk_fma_f32 v[10:11], v[134:135], v[16:17], v[10:11]
	v_lshlrev_b32_e32 v16, 16, v15
	v_and_b32_e32 v17, 0xffff0000, v15
	v_pk_fma_f32 v[10:11], v[150:151], v[16:17], v[10:11]
	v_lshlrev_b32_e32 v44, 16, v0
	v_mul_f32_e32 v1, 0xbfb8aa3b, v10
	v_exp_f32_e32 v1, v1
	v_and_b32_e32 v45, 0xffff0000, v0
	v_and_b32_e32 v5, 0xffff0000, v8
	v_pk_fma_f32 v[2:3], v[152:153], v[6:7], v[2:3]
	v_add_f32_e32 v1, 1.0, v1
	v_rcp_f32_e32 v16, v1
	v_mul_f32_e32 v1, 0xbfb8aa3b, v11
	v_exp_f32_e32 v1, v1
	v_mul_f32_e32 v6, 0xbfb8aa3b, v2
	v_mul_f32_e32 v7, 0xbfb8aa3b, v3
	v_exp_f32_e32 v6, v6
	v_add_f32_e32 v1, 1.0, v1
	v_rcp_f32_e32 v17, v1
	v_pk_fma_f32 v[0:1], v[42:43], v[44:45], 0 op_sel_hi:[1,1,0]
	v_lshlrev_b32_e32 v42, 16, v4
	v_and_b32_e32 v43, 0xffff0000, v4
	v_pk_fma_f32 v[0:1], v[122:123], v[42:43], v[0:1]
	v_lshlrev_b32_e32 v4, 16, v8
	v_pk_fma_f32 v[0:1], v[132:133], v[4:5], v[0:1]
	v_lshlrev_b32_e32 v4, 16, v14
	v_and_b32_e32 v5, 0xffff0000, v14
	v_pk_fma_f32 v[0:1], v[148:149], v[4:5], v[0:1]
	v_exp_f32_e32 v7, v7
	v_mul_f32_e32 v4, 0xbfb8aa3b, v0
	v_mul_f32_e32 v5, 0xbfb8aa3b, v1
	v_exp_f32_e32 v4, v4
	v_exp_f32_e32 v5, v5
	v_add_f32_e32 v6, 1.0, v6
	v_add_f32_e32 v7, 1.0, v7
	v_add_f32_e32 v4, 1.0, v4
	v_add_f32_e32 v5, 1.0, v5
	v_rcp_f32_e32 v4, v4
	v_rcp_f32_e32 v5, v5
	v_rcp_f32_e32 v6, v6
	v_rcp_f32_e32 v7, v7
	v_pk_mul_f32 v[10:11], v[10:11], v[16:17]
	v_pk_mul_f32 v[0:1], v[0:1], v[4:5]
	v_pk_mul_f32 v[16:17], v[10:11], v[10:11]
	v_pk_mul_f32 v[4:5], v[0:1], v[0:1]
	v_pk_mul_f32 v[2:3], v[2:3], v[6:7]
	v_add_f32_e32 v4, v4, v5
	v_add_f32_e32 v4, v16, v4
	v_pk_mul_f32 v[6:7], v[2:3], v[2:3]
	v_add_f32_e32 v4, v17, v4
	v_pk_mul_f32 v[18:19], v[18:19], v[48:49]
	v_add_f32_e32 v4, v6, v4
	v_pk_mul_f32 v[48:49], v[18:19], v[18:19]
	v_add_f32_e32 v4, v7, v4
	v_add_f32_e32 v4, v48, v4
	v_add_f32_e32 v4, v49, v4
	ds_bpermute_b32 v5, v23, v4
	v_add_u32_e32 v8, 31, v24
	v_or_b32_e32 v8, v36, v8
	v_mad_u64_u32 v[8:9], s[0:1], v8, s29, v[12:13]
	s_waitcnt lgkmcnt(0)
	v_add_f32_e32 v4, v4, v5
	ds_bpermute_b32 v5, v109, v4
	v_or3_b32 v14, v24, v36, 32
	v_add_u32_e32 v9, v112, v9
	v_mad_u64_u32 v[14:15], s[0:1], v14, s29, v[12:13]
	s_waitcnt lgkmcnt(0)
	v_add_f32_e32 v4, v4, v5
	ds_bpermute_b32 v5, v110, v4
	v_add_u32_e32 v15, v112, v15
	global_load_dwordx4 v[14:17], v[14:15], off
	s_waitcnt lgkmcnt(0)
	v_add_f32_e32 v4, v4, v5
	ds_bpermute_b32 v5, v111, v4
	s_waitcnt lgkmcnt(0)
	v_add_f32_e32 v4, v4, v5
	v_add_f32_e32 v4, 0x358637bd, v4
	v_cmp_gt_f32_e32 vcc, s70, v4
	v_mul_f32_e32 v5, 0x4b800000, v4
	s_nop 0
	v_cndmask_b32_e32 v4, v4, v5, vcc
	v_rsq_f32_e32 v4, v4
	s_nop 0
	v_mul_f32_e32 v5, 0x45800000, v4
	v_cndmask_b32_e32 v4, v4, v5, vcc
	v_pk_mul_f32 v[0:1], v[0:1], v[4:5] op_sel_hi:[1,0]
	v_pk_mul_f32 v[6:7], v[10:11], v[4:5] op_sel_hi:[1,0]
	v_pk_mul_f32 v[2:3], v[2:3], v[4:5] op_sel_hi:[1,0]
	v_pk_mul_f32 v[4:5], v[18:19], v[4:5] op_sel_hi:[1,0]
	v_cvt_pk_bf16_f32 v2, v2, v3
	v_cvt_pk_bf16_f32 v3, v4, v5
	v_mul_u32_u24_e32 v4, 0x110, v25
	v_cvt_pk_bf16_f32 v0, v0, v1
	v_cvt_pk_bf16_f32 v1, v6, v7
	v_add3_u32 v25, v196, v4, v26
	ds_write_b128 v25, v[0:3] offset:21504
	v_add_u32_e32 v0, 29, v24
	v_or_b32_e32 v0, v36, v0
	v_add_u32_e32 v4, 30, v24
	v_mad_u64_u32 v[0:1], s[0:1], v0, s29, v[12:13]
	v_or_b32_e32 v4, v36, v4
	v_add_u32_e32 v1, v112, v1
	v_mad_u64_u32 v[4:5], s[0:1], v4, s29, v[12:13]
	global_load_dwordx4 v[0:3], v[0:1], off
	v_add_u32_e32 v5, v112, v5
	global_load_dwordx4 v[4:7], v[4:5], off
	s_waitcnt vmcnt(1)
	v_lshlrev_b32_e32 v18, 16, v3
	global_load_dwordx4 v[8:11], v[8:9], off
	ds_read_b128 v[42:45], v108 offset:512
	ds_read_b128 v[118:121], v108 offset:528
	ds_read_b128 v[122:125], v108 offset:1536
	ds_read_b128 v[128:131], v108 offset:1552
	ds_read_b128 v[132:135], v108 offset:2560
	ds_read_b128 v[144:147], v108 offset:2576
	ds_read_b128 v[148:151], v108 offset:3584
	ds_read_b128 v[152:155], v108 offset:3600
	v_and_b32_e32 v19, 0xffff0000, v3
	s_waitcnt lgkmcnt(6)
	v_pk_fma_f32 v[18:19], v[120:121], v[18:19], 0 op_sel_hi:[1,1,0]
	s_waitcnt vmcnt(1)
	v_lshlrev_b32_e32 v48, 16, v7
	v_and_b32_e32 v49, 0xffff0000, v7
	s_waitcnt lgkmcnt(4)
	v_pk_fma_f32 v[18:19], v[130:131], v[48:49], v[18:19]
	v_lshlrev_b32_e32 v114, 16, v2
	v_and_b32_e32 v115, 0xffff0000, v2
	s_waitcnt vmcnt(0)
	v_lshlrev_b32_e32 v48, 16, v11
	v_and_b32_e32 v49, 0xffff0000, v11
	s_waitcnt lgkmcnt(2)
	v_pk_fma_f32 v[18:19], v[146:147], v[48:49], v[18:19]
	v_lshlrev_b32_e32 v48, 16, v17
	v_and_b32_e32 v49, 0xffff0000, v17
	s_waitcnt lgkmcnt(0)
	v_pk_fma_f32 v[18:19], v[154:155], v[48:49], v[18:19]
	v_and_b32_e32 v7, 0xffff0000, v10
	v_mul_f32_e32 v3, 0xbfb8aa3b, v18
	v_exp_f32_e32 v3, v3
	v_and_b32_e32 v11, 0xffff0000, v1
	v_and_b32_e32 v17, 0xffff0000, v5
	v_add_f32_e32 v3, 1.0, v3
	v_rcp_f32_e32 v48, v3
	v_mul_f32_e32 v3, 0xbfb8aa3b, v19
	v_exp_f32_e32 v3, v3
	s_nop 0
	v_add_f32_e32 v3, 1.0, v3
	v_rcp_f32_e32 v49, v3
	v_pk_fma_f32 v[2:3], v[118:119], v[114:115], 0 op_sel_hi:[1,1,0]
	v_lshlrev_b32_e32 v114, 16, v6
	v_and_b32_e32 v115, 0xffff0000, v6
	v_pk_fma_f32 v[2:3], v[128:129], v[114:115], v[2:3]
	v_lshlrev_b32_e32 v6, 16, v10
	v_lshlrev_b32_e32 v10, 16, v1
	v_pk_fma_f32 v[2:3], v[144:145], v[6:7], v[2:3]
	v_lshlrev_b32_e32 v6, 16, v16
	v_and_b32_e32 v7, 0xffff0000, v16
	v_pk_fma_f32 v[10:11], v[44:45], v[10:11], 0 op_sel_hi:[1,1,0]
	v_lshlrev_b32_e32 v16, 16, v5
	v_pk_fma_f32 v[10:11], v[124:125], v[16:17], v[10:11]
	v_lshlrev_b32_e32 v16, 16, v9
	v_and_b32_e32 v17, 0xffff0000, v9
	v_pk_fma_f32 v[10:11], v[134:135], v[16:17], v[10:11]
	v_lshlrev_b32_e32 v16, 16, v15
	v_and_b32_e32 v17, 0xffff0000, v15
	v_pk_fma_f32 v[10:11], v[150:151], v[16:17], v[10:11]
	v_lshlrev_b32_e32 v44, 16, v0
	v_mul_f32_e32 v1, 0xbfb8aa3b, v10
	v_exp_f32_e32 v1, v1
	v_and_b32_e32 v45, 0xffff0000, v0
	v_and_b32_e32 v5, 0xffff0000, v8
	v_pk_fma_f32 v[2:3], v[152:153], v[6:7], v[2:3]
	v_add_f32_e32 v1, 1.0, v1
	v_rcp_f32_e32 v16, v1
	v_mul_f32_e32 v1, 0xbfb8aa3b, v11
	v_exp_f32_e32 v1, v1
	v_mul_f32_e32 v6, 0xbfb8aa3b, v2
	v_mul_f32_e32 v7, 0xbfb8aa3b, v3
	v_exp_f32_e32 v6, v6
	v_add_f32_e32 v1, 1.0, v1
	v_rcp_f32_e32 v17, v1
	v_pk_fma_f32 v[0:1], v[42:43], v[44:45], 0 op_sel_hi:[1,1,0]
	v_lshlrev_b32_e32 v42, 16, v4
	v_and_b32_e32 v43, 0xffff0000, v4
	v_pk_fma_f32 v[0:1], v[122:123], v[42:43], v[0:1]
	v_lshlrev_b32_e32 v4, 16, v8
	v_pk_fma_f32 v[0:1], v[132:133], v[4:5], v[0:1]
	v_lshlrev_b32_e32 v4, 16, v14
	v_and_b32_e32 v5, 0xffff0000, v14
	v_pk_fma_f32 v[0:1], v[148:149], v[4:5], v[0:1]
	v_exp_f32_e32 v7, v7
	v_mul_f32_e32 v4, 0xbfb8aa3b, v0
	v_mul_f32_e32 v5, 0xbfb8aa3b, v1
	v_exp_f32_e32 v4, v4
	v_exp_f32_e32 v5, v5
	v_add_f32_e32 v6, 1.0, v6
	v_add_f32_e32 v7, 1.0, v7
	v_add_f32_e32 v4, 1.0, v4
	v_add_f32_e32 v5, 1.0, v5
	v_rcp_f32_e32 v4, v4
	v_rcp_f32_e32 v5, v5
	v_rcp_f32_e32 v6, v6
	v_rcp_f32_e32 v7, v7
	v_pk_mul_f32 v[10:11], v[10:11], v[16:17]
	v_pk_mul_f32 v[0:1], v[0:1], v[4:5]
	v_pk_mul_f32 v[16:17], v[10:11], v[10:11]
	v_pk_mul_f32 v[4:5], v[0:1], v[0:1]
	v_pk_mul_f32 v[2:3], v[2:3], v[6:7]
	v_add_f32_e32 v4, v4, v5
	v_add_f32_e32 v4, v16, v4
	v_pk_mul_f32 v[6:7], v[2:3], v[2:3]
	v_add_f32_e32 v4, v17, v4
	v_pk_mul_f32 v[18:19], v[18:19], v[48:49]
	v_add_f32_e32 v4, v6, v4
	v_pk_mul_f32 v[48:49], v[18:19], v[18:19]
	v_add_f32_e32 v4, v7, v4
	v_add_f32_e32 v4, v48, v4
	v_add_f32_e32 v4, v49, v4
	ds_bpermute_b32 v5, v23, v4
	v_bfe_u32 v8, v38, 4, 4
	s_waitcnt lgkmcnt(0)
	v_add_f32_e32 v4, v4, v5
	ds_bpermute_b32 v5, v109, v4
	s_waitcnt lgkmcnt(0)
	v_add_f32_e32 v4, v4, v5
	ds_bpermute_b32 v5, v110, v4
	s_waitcnt lgkmcnt(0)
	v_add_f32_e32 v4, v4, v5
	ds_bpermute_b32 v5, v111, v4
	s_waitcnt lgkmcnt(0)
	v_add_f32_e32 v4, v4, v5
	v_add_f32_e32 v4, 0x358637bd, v4
	v_cmp_gt_f32_e32 vcc, s70, v4
	v_mul_f32_e32 v5, 0x4b800000, v4
	s_nop 0
	v_cndmask_b32_e32 v4, v4, v5, vcc
	v_rsq_f32_e32 v4, v4
	s_nop 0
	v_mul_f32_e32 v5, 0x45800000, v4
	v_cndmask_b32_e32 v4, v4, v5, vcc
	v_pk_mul_f32 v[0:1], v[0:1], v[4:5] op_sel_hi:[1,0]
	v_pk_mul_f32 v[6:7], v[10:11], v[4:5] op_sel_hi:[1,0]
	v_pk_mul_f32 v[2:3], v[2:3], v[4:5] op_sel_hi:[1,0]
	v_pk_mul_f32 v[4:5], v[18:19], v[4:5] op_sel_hi:[1,0]
	v_cvt_pk_bf16_f32 v0, v0, v1
	v_cvt_pk_bf16_f32 v1, v6, v7
	v_cvt_pk_bf16_f32 v2, v2, v3
	v_cvt_pk_bf16_f32 v3, v4, v5
	ds_write_b128 v25, v[0:3] offset:25856
	v_add_u32_e32 v0, 45, v8
	v_or_b32_e32 v0, v36, v0
	v_add_u32_e32 v4, 46, v8
	v_or_b32_e32 v25, 48, v8
	v_mad_u64_u32 v[0:1], s[0:1], v0, s29, v[12:13]
	v_or_b32_e32 v4, v36, v4
	v_add_u32_e32 v8, 47, v8
	v_add_u32_e32 v1, v112, v1
	v_mad_u64_u32 v[4:5], s[0:1], v4, s29, v[12:13]
	v_or_b32_e32 v8, v36, v8
	global_load_dwordx4 v[0:3], v[0:1], off
	v_add_u32_e32 v5, v112, v5
	v_mad_u64_u32 v[8:9], s[0:1], v8, s29, v[12:13]
	v_or_b32_e32 v14, v36, v25
	global_load_dwordx4 v[4:7], v[4:5], off
	v_add_u32_e32 v9, v112, v9
	v_mad_u64_u32 v[12:13], s[0:1], v14, s29, v[12:13]
	global_load_dwordx4 v[8:11], v[8:9], off
	v_add_u32_e32 v13, v112, v13
	global_load_dwordx4 v[12:15], v[12:13], off
	ds_read_b128 v[16:19], v108 offset:512
	ds_read_b128 v[42:45], v108 offset:528
	ds_read_b128 v[112:115], v108 offset:1536
	ds_read_b128 v[118:121], v108 offset:1552
	ds_read_b128 v[122:125], v108 offset:2560
	ds_read_b128 v[128:131], v108 offset:2576
	ds_read_b128 v[132:135], v108 offset:3584
	ds_read_b128 v[144:147], v108 offset:3600
	s_waitcnt vmcnt(3)
	v_lshlrev_b32_e32 v48, 16, v3
	v_and_b32_e32 v49, 0xffff0000, v3
	s_waitcnt lgkmcnt(6)
	v_pk_fma_f32 v[44:45], v[44:45], v[48:49], 0 op_sel_hi:[1,1,0]
	s_waitcnt vmcnt(2)
	v_lshlrev_b32_e32 v48, 16, v7
	v_and_b32_e32 v49, 0xffff0000, v7
	s_waitcnt lgkmcnt(4)
	v_pk_fma_f32 v[44:45], v[120:121], v[48:49], v[44:45]
	v_lshlrev_b32_e32 v120, 16, v2
	s_waitcnt vmcnt(1)
	v_lshlrev_b32_e32 v48, 16, v11
	v_and_b32_e32 v49, 0xffff0000, v11
	s_waitcnt lgkmcnt(2)
	v_pk_fma_f32 v[44:45], v[130:131], v[48:49], v[44:45]
	s_waitcnt vmcnt(0)
	v_lshlrev_b32_e32 v48, 16, v15
	v_and_b32_e32 v49, 0xffff0000, v15
	s_waitcnt lgkmcnt(0)
	v_pk_fma_f32 v[44:45], v[146:147], v[48:49], v[44:45]
	v_and_b32_e32 v121, 0xffff0000, v2
	v_mul_f32_e32 v3, 0xbfb8aa3b, v44
	v_exp_f32_e32 v3, v3
	v_and_b32_e32 v7, 0xffff0000, v10
	v_and_b32_e32 v11, 0xffff0000, v1
	v_and_b32_e32 v15, 0xffff0000, v5
	v_add_f32_e32 v3, 1.0, v3
	v_rcp_f32_e32 v48, v3
	v_mul_f32_e32 v3, 0xbfb8aa3b, v45
	v_exp_f32_e32 v3, v3
	s_nop 0
	v_add_f32_e32 v3, 1.0, v3
	v_rcp_f32_e32 v49, v3
	v_pk_fma_f32 v[2:3], v[42:43], v[120:121], 0 op_sel_hi:[1,1,0]
	v_lshlrev_b32_e32 v42, 16, v6
	v_and_b32_e32 v43, 0xffff0000, v6
	v_pk_fma_f32 v[2:3], v[118:119], v[42:43], v[2:3]
	v_lshlrev_b32_e32 v6, 16, v10
	v_lshlrev_b32_e32 v10, 16, v1
	v_pk_fma_f32 v[2:3], v[128:129], v[6:7], v[2:3]
	v_lshlrev_b32_e32 v6, 16, v14
	v_and_b32_e32 v7, 0xffff0000, v14
	v_pk_fma_f32 v[10:11], v[18:19], v[10:11], 0 op_sel_hi:[1,1,0]
	v_lshlrev_b32_e32 v14, 16, v5
	v_pk_fma_f32 v[10:11], v[114:115], v[14:15], v[10:11]
	v_lshlrev_b32_e32 v14, 16, v9
	v_and_b32_e32 v15, 0xffff0000, v9
	v_pk_fma_f32 v[10:11], v[124:125], v[14:15], v[10:11]
	v_lshlrev_b32_e32 v14, 16, v13
	v_and_b32_e32 v15, 0xffff0000, v13
	v_pk_fma_f32 v[10:11], v[134:135], v[14:15], v[10:11]
	v_lshlrev_b32_e32 v18, 16, v0
	v_mul_f32_e32 v1, 0xbfb8aa3b, v10
	v_exp_f32_e32 v1, v1
	v_and_b32_e32 v19, 0xffff0000, v0
	v_and_b32_e32 v5, 0xffff0000, v8
	v_pk_fma_f32 v[2:3], v[144:145], v[6:7], v[2:3]
	v_add_f32_e32 v1, 1.0, v1
	v_rcp_f32_e32 v14, v1
	v_mul_f32_e32 v1, 0xbfb8aa3b, v11
	v_exp_f32_e32 v1, v1
	v_mul_f32_e32 v6, 0xbfb8aa3b, v2
	v_mul_f32_e32 v7, 0xbfb8aa3b, v3
	v_exp_f32_e32 v6, v6
	v_add_f32_e32 v1, 1.0, v1
	v_rcp_f32_e32 v15, v1
	v_pk_fma_f32 v[0:1], v[16:17], v[18:19], 0 op_sel_hi:[1,1,0]
	v_lshlrev_b32_e32 v16, 16, v4
	v_and_b32_e32 v17, 0xffff0000, v4
	v_pk_fma_f32 v[0:1], v[112:113], v[16:17], v[0:1]
	v_lshlrev_b32_e32 v4, 16, v8
	v_pk_fma_f32 v[0:1], v[122:123], v[4:5], v[0:1]
	v_lshlrev_b32_e32 v4, 16, v12
	v_and_b32_e32 v5, 0xffff0000, v12
	v_pk_fma_f32 v[0:1], v[132:133], v[4:5], v[0:1]
	v_exp_f32_e32 v7, v7
	v_mul_f32_e32 v4, 0xbfb8aa3b, v0
	v_mul_f32_e32 v5, 0xbfb8aa3b, v1
	v_exp_f32_e32 v4, v4
	v_exp_f32_e32 v5, v5
	v_add_f32_e32 v6, 1.0, v6
	v_add_f32_e32 v7, 1.0, v7
	v_add_f32_e32 v4, 1.0, v4
	v_add_f32_e32 v5, 1.0, v5
	v_rcp_f32_e32 v4, v4
	v_rcp_f32_e32 v5, v5
	v_rcp_f32_e32 v6, v6
	v_rcp_f32_e32 v7, v7
	v_pk_mul_f32 v[10:11], v[10:11], v[14:15]
	v_pk_mul_f32 v[0:1], v[0:1], v[4:5]
	v_pk_mul_f32 v[14:15], v[10:11], v[10:11]
	v_pk_mul_f32 v[4:5], v[0:1], v[0:1]
	v_pk_mul_f32 v[2:3], v[2:3], v[6:7]
	v_add_f32_e32 v4, v4, v5
	v_add_f32_e32 v4, v14, v4
	v_pk_mul_f32 v[6:7], v[2:3], v[2:3]
	v_add_f32_e32 v4, v15, v4
	v_pk_mul_f32 v[44:45], v[44:45], v[48:49]
	v_add_f32_e32 v4, v6, v4
	v_pk_mul_f32 v[48:49], v[44:45], v[44:45]
	v_add_f32_e32 v4, v7, v4
	v_add_f32_e32 v4, v48, v4
	v_add_f32_e32 v4, v49, v4
	ds_bpermute_b32 v5, v23, v4
	v_lshlrev_b32_e32 v16, 5, v40
	s_waitcnt lgkmcnt(0)
	v_add_f32_e32 v4, v4, v5
	ds_bpermute_b32 v5, v109, v4
	s_waitcnt lgkmcnt(0)
	v_add_f32_e32 v4, v4, v5
	ds_bpermute_b32 v5, v110, v4
	s_waitcnt lgkmcnt(0)
	v_add_f32_e32 v4, v4, v5
	ds_bpermute_b32 v5, v111, v4
	s_waitcnt lgkmcnt(0)
	v_add_f32_e32 v4, v4, v5
	v_add_f32_e32 v4, 0x358637bd, v4
	v_cmp_gt_f32_e32 vcc, s70, v4
	v_mul_f32_e32 v5, 0x4b800000, v4
	s_nop 0
	v_cndmask_b32_e32 v4, v4, v5, vcc
	v_rsq_f32_e32 v4, v4
	s_nop 0
	v_mul_f32_e32 v5, 0x45800000, v4
	v_cndmask_b32_e32 v4, v4, v5, vcc
	v_pk_mul_f32 v[0:1], v[0:1], v[4:5] op_sel_hi:[1,0]
	v_pk_mul_f32 v[6:7], v[10:11], v[4:5] op_sel_hi:[1,0]
	v_pk_mul_f32 v[2:3], v[2:3], v[4:5] op_sel_hi:[1,0]
	v_pk_mul_f32 v[4:5], v[44:45], v[4:5] op_sel_hi:[1,0]
	v_cvt_pk_bf16_f32 v2, v2, v3
	v_cvt_pk_bf16_f32 v3, v4, v5
	v_mul_u32_u24_e32 v4, 0x110, v25
	v_cvt_pk_bf16_f32 v0, v0, v1
	v_cvt_pk_bf16_f32 v1, v6, v7
	v_add3_u32 v4, v196, v4, v26
	ds_write_b128 v4, v[0:3] offset:21504
	v_cmp_lt_u32_e32 vcc, 1, v20
	v_add_u32_e32 v2, 0x5400, v196
	s_and_saveexec_b64 s[0:1], vcc
	s_xor_b64 s[0:1], exec, s[0:1]
	v_add_u32_e32 v2, 0x1000, v196
	v_lshlrev_b32_e32 v16, 5, v40
	s_or_saveexec_b64 s[0:1], s[0:1]
	v_mov_b32_e32 v23, v37
	v_and_b32_e32 v14, 63, v38
	v_add_u32_e32 v15, 0x11800, v196
	v_add_u32_e32 v12, 0x11c00, v196
	v_add_u32_e32 v13, 0x11a00, v196
	v_mov_b32_e32 v0, 0xc800
	s_xor_b64 exec, exec, s[0:1]
	s_cbranch_execz .LBB0_293
	v_or_b32_e32 v3, v107, v20
	v_lshlrev_b32_e32 v20, 16, v3
	v_lshl_add_u64 v[0:1], s[16:17], 0, v[20:21]
	v_lshlrev_b64 v[4:5], 2, v[22:23]
	v_lshl_add_u64 v[6:7], v[0:1], 0, v[4:5]
	v_lshl_add_u64 v[4:5], s[16:17], 0, v[4:5]
	v_lshlrev_b32_e32 v0, 2, v14
	v_mov_b32_e32 v1, v21
	v_lshl_add_u64 v[4:5], v[4:5], 0, v[20:21]
	v_lshl_add_u64 v[4:5], v[4:5], 0, v[0:1]
	v_add_co_u32_e32 v4, vcc, 0x200000, v4
	v_lshl_add_u64 v[6:7], v[6:7], 0, v[0:1]
	s_nop 0
	v_addc_co_u32_e32 v5, vcc, 0, v5, vcc
	v_readlane_b32 s36, v250, 19
	global_load_dword v7, v[6:7], off
	v_readlane_b32 s37, v250, 20
	global_load_dword v4, v[4:5], off
	v_lshlrev_b32_e32 v6, 2, v3
	s_mov_b32 s2, 0xbfb8aa3b
	v_readlane_b32 s38, v250, 21
	v_readlane_b32 s39, v250, 22
	global_load_dword v5, v6, s[36:37]
	v_readlane_b32 s40, v250, 23
	v_readlane_b32 s41, v250, 24
	v_readlane_b32 s42, v250, 25
	v_readlane_b32 s43, v250, 26
	v_readlane_b32 s44, v250, 27
	v_readlane_b32 s45, v250, 28
	v_readlane_b32 s46, v250, 29
	v_readlane_b32 s47, v250, 30
	v_readlane_b32 s48, v250, 31
	v_readlane_b32 s49, v250, 32
	v_readlane_b32 s50, v250, 33
	v_readlane_b32 s51, v250, 34
	v_readlane_b32 s36, v250, 3
	v_readlane_b32 s50, v250, 17
	v_readlane_b32 s51, v250, 18
	v_readlane_b32 s4, v250, 41
	v_readlane_b32 s5, v250, 42
	v_readlane_b32 s37, v250, 4
	v_readlane_b32 s38, v250, 5
	v_readlane_b32 s39, v250, 6
	global_load_dword v6, v6, s[50:51]
	v_readlane_b32 s40, v250, 7
	v_readlane_b32 s41, v250, 8
	v_readlane_b32 s42, v250, 9
	v_readlane_b32 s43, v250, 10
	v_readlane_b32 s44, v250, 11
	v_readlane_b32 s45, v250, 12
	v_readlane_b32 s46, v250, 13
	v_readlane_b32 s47, v250, 14
	v_readlane_b32 s48, v250, 15
	v_readlane_b32 s49, v250, 16
	s_waitcnt vmcnt(2)
	v_mul_f32_e32 v4, 0xbfb8aa3b, v4
	v_exp_f32_e32 v4, v4
	s_waitcnt vmcnt(1)
	v_add_f32_e32 v5, v7, v5
	v_mul_f32_e64 v8, |v5|, s2
	v_fma_f32 v9, |v5|, s2, -v8
	s_mov_b32 s2, 0xb2a5705f
	v_rndne_f32_e32 v10, v8
	v_fma_f32 v9, |v5|, s2, v9
	v_sub_f32_e32 v8, v8, v10
	v_add_f32_e32 v8, v8, v9
	v_exp_f32_e32 v8, v8
	v_cvt_i32_f32_e32 v9, v10
	s_mov_b32 s2, 0x42ce8ed0
	v_cmp_ngt_f32_e64 vcc, |v5|, s2
	s_mov_b32 s2, 0xc2b17218
	v_ldexp_f32 v8, v8, v9
	v_cndmask_b32_e32 v8, 0, v8, vcc
	v_cmp_nlt_f32_e64 vcc, |v5|, s2
	v_max_f32_e32 v7, 0, v5
	s_mov_b32 s2, 0x3f2aaaab
	v_cndmask_b32_e32 v5, v193, v8, vcc
	v_add_f32_e32 v10, 1.0, v5
	v_add_f32_e32 v8, -1.0, v10
	v_sub_f32_e32 v9, v8, v10
	v_add_f32_e32 v9, 1.0, v9
	v_sub_f32_e32 v8, v5, v8
	v_add_f32_e32 v11, v8, v9
	v_frexp_mant_f32_e32 v8, v10
	v_cmp_gt_f32_e32 vcc, s2, v8
	v_cvt_f64_f32_e32 v[8:9], v10
	v_frexp_exp_i32_f64_e32 v8, v[8:9]
	v_subbrev_co_u32_e32 v8, vcc, 0, v8, vcc
	v_sub_u32_e32 v9, 0, v8
	v_ldexp_f32 v10, v10, v9
	v_ldexp_f32 v9, v11, v9
	v_add_f32_e32 v11, -1.0, v10
	v_add_f32_e32 v17, 1.0, v11
	v_sub_f32_e32 v17, v10, v17
	v_add_f32_e32 v17, v9, v17
	v_add_f32_e32 v18, v11, v17
	v_sub_f32_e32 v11, v11, v18
	v_add_f32_e32 v11, v17, v11
	v_add_f32_e32 v17, 1.0, v10
	v_add_f32_e32 v19, -1.0, v17
	v_sub_f32_e32 v10, v10, v19
	v_add_f32_e32 v9, v9, v10
	v_add_f32_e32 v10, v17, v9
	v_sub_f32_e32 v17, v17, v10
	v_add_f32_e32 v9, v9, v17
	v_rcp_f32_e32 v17, v10
	v_cvt_f32_i32_e32 v8, v8
	s_mov_b32 s2, 0x3f317218
	v_add_f32_e32 v4, 1.0, v4
	v_mul_f32_e32 v19, v18, v17
	v_mul_f32_e32 v20, v10, v19
	v_fma_f32 v25, v19, v10, -v20
	v_fmac_f32_e32 v25, v19, v9
	v_add_f32_e32 v36, v20, v25
	v_sub_f32_e32 v40, v18, v36
	v_sub_f32_e32 v18, v18, v40
	v_sub_f32_e32 v20, v36, v20
	v_sub_f32_e32 v18, v18, v36
	v_add_f32_e32 v11, v11, v18
	v_sub_f32_e32 v18, v20, v25
	v_add_f32_e32 v11, v18, v11
	v_add_f32_e32 v18, v40, v11
	v_mul_f32_e32 v20, v17, v18
	v_mul_f32_e32 v25, v10, v20
	v_fma_f32 v10, v20, v10, -v25
	v_fmac_f32_e32 v10, v20, v9
	v_sub_f32_e32 v9, v40, v18
	v_add_f32_e32 v9, v11, v9
	v_add_f32_e32 v11, v25, v10
	v_sub_f32_e32 v36, v18, v11
	v_sub_f32_e32 v18, v18, v36
	v_sub_f32_e32 v25, v11, v25
	v_sub_f32_e32 v11, v18, v11
	v_add_f32_e32 v9, v9, v11
	v_sub_f32_e32 v10, v25, v10
	v_add_f32_e32 v9, v10, v9
	v_add_f32_e32 v10, v19, v20
	v_add_f32_e32 v9, v36, v9
	v_sub_f32_e32 v11, v10, v19
	v_mul_f32_e32 v9, v17, v9
	v_sub_f32_e32 v11, v20, v11
	v_add_f32_e32 v9, v11, v9
	v_mul_f32_e32 v19, 0x3f317218, v8
	v_add_f32_e32 v11, v10, v9
	v_fma_f32 v20, v8, s2, -v19
	v_mul_f32_e32 v17, v11, v11
	v_fmac_f32_e32 v20, 0xb102e308, v8
	v_sub_f32_e32 v8, v11, v10
	v_fmamk_f32 v18, v17, 0x3e9b6dac, v188
	v_sub_f32_e32 v8, v9, v8
	v_add_f32_e32 v9, v19, v20
	v_fmaak_f32 v18, v17, v18, 0x3f2aaada
	v_sub_f32_e32 v10, v9, v19
	v_ldexp_f32 v19, v11, 1
	v_mul_f32_e32 v11, v11, v17
	v_mul_f32_e32 v11, v11, v18
	v_add_f32_e32 v17, v19, v11
	v_sub_f32_e32 v18, v17, v19
	v_ldexp_f32 v8, v8, 1
	v_sub_f32_e32 v11, v11, v18
	v_add_f32_e32 v8, v8, v11
	v_add_f32_e32 v11, v17, v8
	v_sub_f32_e32 v17, v11, v17
	v_sub_f32_e32 v8, v8, v17
	v_add_f32_e32 v17, v9, v11
	v_sub_f32_e32 v18, v17, v9
	v_sub_f32_e32 v19, v17, v18
	v_sub_f32_e32 v10, v20, v10
	v_sub_f32_e32 v9, v9, v19
	v_sub_f32_e32 v11, v11, v18
	v_add_f32_e32 v9, v11, v9
	v_add_f32_e32 v11, v10, v8
	v_sub_f32_e32 v18, v11, v10
	v_sub_f32_e32 v19, v11, v18
	v_sub_f32_e32 v10, v10, v19
	v_sub_f32_e32 v8, v8, v18
	v_add_f32_e32 v9, v11, v9
	v_add_f32_e32 v8, v8, v10
	v_add_f32_e32 v10, v17, v9
	v_sub_f32_e32 v11, v10, v17
	v_sub_f32_e32 v9, v9, v11
	v_add_f32_e32 v8, v8, v9
	s_mov_b32 s2, 0x7f800000
	v_add_f32_e32 v8, v10, v8
	v_cmp_neq_f32_e32 vcc, s2, v5
	s_mov_b32 s2, 0x33800000
	v_rcp_f32_e32 v4, v4
	v_cndmask_b32_e32 v8, v193, v8, vcc
	v_cmp_lt_f32_e64 vcc, |v5|, s2
	s_mov_b32 s2, 0x3fb8aa3b
	v_lshlrev_b32_e32 v20, 2, v39
	v_cndmask_b32_e32 v5, v8, v5, vcc
	v_add_f32_e32 v5, v7, v5
	s_waitcnt vmcnt(0)
	v_mul_f32_e32 v7, 0x3fb8aa3b, v6
	v_fma_f32 v8, v6, s2, -v7
	v_rndne_f32_e32 v9, v7
	v_fmac_f32_e32 v8, 0x32a5705f, v6
	v_sub_f32_e32 v7, v7, v9
	v_add_f32_e32 v7, v7, v8
	v_exp_f32_e32 v7, v7
	v_cvt_i32_f32_e32 v8, v9
	s_mov_b32 s2, 0xc2ce8ed0
	v_cmp_ngt_f32_e32 vcc, s2, v6
	s_mov_b32 s2, 0x42b17218
	v_ldexp_f32 v7, v7, v8
	v_cndmask_b32_e32 v7, 0, v7, vcc
	v_cmp_nlt_f32_e32 vcc, s2, v6
	v_add_u32_e32 v8, -1, v191
	s_nop 0
	v_cndmask_b32_e32 v7, v193, v7, vcc
	v_cmp_lt_i32_e32 vcc, v8, v47
	v_mul_f32_e64 v6, v5, -v7
	s_nop 0
	v_cndmask_b32_e32 v8, v8, v191, vcc
	v_lshlrev_b32_e32 v8, 2, v8
	ds_bpermute_b32 v8, v8, v6
	v_cmp_eq_u32_e32 vcc, 0, v14
	s_waitcnt lgkmcnt(0)
	v_fma_f32 v5, v5, -v7, v8
	v_cndmask_b32_e32 v5, v5, v6, vcc
	v_add_u32_e32 v6, -2, v191
	v_cmp_lt_i32_e32 vcc, v6, v47
	s_nop 1
	v_cndmask_b32_e32 v6, v6, v191, vcc
	v_lshlrev_b32_e32 v6, 2, v6
	ds_bpermute_b32 v6, v6, v5
	v_cmp_gt_u32_e32 vcc, 2, v14
	s_waitcnt lgkmcnt(0)
	v_add_f32_e32 v6, v5, v6
	v_cndmask_b32_e32 v5, v6, v5, vcc
	v_add_u32_e32 v6, -4, v191
	v_cmp_lt_i32_e32 vcc, v6, v47
	s_nop 1
	v_cndmask_b32_e32 v6, v6, v191, vcc
	v_lshlrev_b32_e32 v6, 2, v6
	ds_bpermute_b32 v6, v6, v5
	v_cmp_gt_u32_e32 vcc, 4, v14
	s_waitcnt lgkmcnt(0)
	v_add_f32_e32 v6, v5, v6
	v_cndmask_b32_e32 v5, v6, v5, vcc
	v_add_u32_e32 v6, -8, v191
	v_cmp_lt_i32_e32 vcc, v6, v47
	s_nop 1
	v_cndmask_b32_e32 v6, v6, v191, vcc
	v_lshlrev_b32_e32 v6, 2, v6
	ds_bpermute_b32 v6, v6, v5
	v_cmp_gt_u32_e32 vcc, 8, v14
	s_waitcnt lgkmcnt(0)
	v_add_f32_e32 v6, v5, v6
	v_cndmask_b32_e32 v5, v6, v5, vcc
	v_add_u32_e32 v6, -16, v191
	v_cmp_lt_i32_e32 vcc, v6, v47
	s_nop 1
	v_cndmask_b32_e32 v6, v6, v191, vcc
	v_lshlrev_b32_e32 v6, 2, v6
	ds_bpermute_b32 v6, v6, v5
	v_cmp_gt_u32_e32 vcc, 16, v14
	s_waitcnt lgkmcnt(0)
	v_add_f32_e32 v6, v5, v6
	v_cndmask_b32_e32 v5, v6, v5, vcc
	v_subrev_u32_e32 v6, 32, v191
	v_cmp_lt_i32_e32 vcc, v6, v47
	s_nop 1
	v_cndmask_b32_e32 v6, v6, v191, vcc
	v_lshlrev_b32_e32 v6, 2, v6
	ds_bpermute_b32 v6, v6, v5
	v_cmp_gt_u32_e32 vcc, 32, v14
	s_waitcnt lgkmcnt(0)
	v_add_f32_e32 v6, v5, v6
	v_cndmask_b32_e32 v6, v6, v5, vcc
	v_lshlrev_b32_e32 v5, 2, v194
	v_add_u32_e32 v7, v15, v5
	ds_write_b32 v7, v6
	v_add_u32_e32 v7, v13, v5
	ds_write_b32 v7, v4
	v_mul_f32_e32 v7, 0x3fb8aa3b, v6
	v_exp_f32_e32 v7, v7
	v_add_u32_e32 v5, v12, v5
	v_mul_f32_e32 v4, v4, v7
	ds_write_b32 v5, v4
	v_or_b32_e32 v4, v3, v16
	v_ashrrev_i32_e32 v5, 31, v4
	v_lshlrev_b64 v[4:5], 15, v[4:5]
	v_lshl_add_u64 v[4:5], s[4:5], 0, v[4:5]
	v_lshl_add_u64 v[4:5], v[4:5], 0, v[20:21]
	v_lshl_add_u64 v[0:1], v[4:5], 0, v[0:1]
	global_store_dword v[0:1], v6, off
	v_mov_b32_e32 v0, 0x8800

	.amdhsa_kernel _Z9mk_kernelILin1EEv6Params
		.amdhsa_group_segment_fixed_size 0
		.amdhsa_private_segment_fixed_size 0
		.amdhsa_kernarg_size 416
		.amdhsa_user_sgpr_count 2
		.amdhsa_user_sgpr_dispatch_ptr 0
		.amdhsa_user_sgpr_queue_ptr 0
		.amdhsa_user_sgpr_kernarg_segment_ptr 1
		.amdhsa_user_sgpr_dispatch_id 0
		.amdhsa_user_sgpr_kernarg_preload_length 0
		.amdhsa_user_sgpr_kernarg_preload_offset 0
		.amdhsa_user_sgpr_private_segment_size 0
		.amdhsa_uses_dynamic_stack 0
		.amdhsa_enable_private_segment 0
		.amdhsa_system_sgpr_workgroup_id_x 1
		.amdhsa_system_sgpr_workgroup_id_y 0
		.amdhsa_system_sgpr_workgroup_id_z 0
		.amdhsa_system_sgpr_workgroup_info 0
		.amdhsa_system_vgpr_workitem_id 2
		.amdhsa_next_free_vgpr 255
		.amdhsa_next_free_sgpr 102
		.amdhsa_accum_offset 256
		.amdhsa_reserve_vcc 1
		.amdhsa_float_round_mode_32 0
		.amdhsa_float_round_mode_16_64 0
		.amdhsa_float_denorm_mode_32 3
		.amdhsa_float_denorm_mode_16_64 3
		.amdhsa_dx10_clamp 1
		.amdhsa_ieee_mode 1
		.amdhsa_fp16_overflow 0
		.amdhsa_tg_split 0
		.amdhsa_exception_fp_ieee_invalid_op 0
		.amdhsa_exception_fp_denorm_src 0
		.amdhsa_exception_fp_ieee_div_zero 0
		.amdhsa_exception_fp_ieee_overflow 0
		.amdhsa_exception_fp_ieee_underflow 0
		.amdhsa_exception_fp_ieee_inexact 0
		.amdhsa_exception_int_div_zero 0
	.end_amdhsa_kernel

amdhsa.kernels:
  - .agpr_count:     0
    .args:
      - .offset:         0
        .size:           160
        .value_kind:     by_value
      - .offset:         160
        .size:           4
        .value_kind:     hidden_block_count_x
      - .offset:         164
        .size:           4
        .value_kind:     hidden_block_count_y
      - .offset:         168
        .size:           4
        .value_kind:     hidden_block_count_z
      - .offset:         172
        .size:           2
        .value_kind:     hidden_group_size_x
      - .offset:         174
        .size:           2
        .value_kind:     hidden_group_size_y
      - .offset:         176
        .size:           2
        .value_kind:     hidden_group_size_z
      - .offset:         178
        .size:           2
        .value_kind:     hidden_remainder_x
      - .offset:         180
        .size:           2
        .value_kind:     hidden_remainder_y
      - .offset:         182
        .size:           2
        .value_kind:     hidden_remainder_z
      - .offset:         200
        .size:           8
        .value_kind:     hidden_global_offset_x
      - .offset:         208
        .size:           8
        .value_kind:     hidden_global_offset_y
      - .offset:         216
        .size:           8
        .value_kind:     hidden_global_offset_z
      - .offset:         224
        .size:           2
        .value_kind:     hidden_grid_dims
      - .offset:         248
        .size:           8
        .value_kind:     hidden_multigrid_sync_arg
      - .offset:         280
        .size:           4
        .value_kind:     hidden_dynamic_lds_size
    .group_segment_fixed_size: 0
    .kernarg_segment_align: 8
    .kernarg_segment_size: 416
    .language:       OpenCL C
    .language_version:
      - 2
      - 0
    .max_flat_workgroup_size: 512
    .name:           _Z9mk_kernelILin1EEv6Params
    .private_segment_fixed_size: 0
    .sgpr_count:     108
    .sgpr_spill_count: 62
    .symbol:         _Z9mk_kernelILin1EEv6Params.kd
    .uniform_work_group_size: 1
    .uses_dynamic_stack: false
    .vgpr_count:     255
    .vgpr_spill_count: 0
    .wavefront_size: 64
